# GEMM k-loops: 44 duplicated lgkmcnt(0) waits (compiler copy right after the hand-placed one) removed
# speedup vs baseline: 1.0092x; 1.0001x over previous
.LBB0_283:
	ds_read_b128 v[170:173], v160
	ds_read_b128 v[174:177], v160 offset:1024
	ds_read_b128 v[178:181], v160 offset:2048
	ds_read_b128 v[182:185], v160 offset:3072
	v_add_u32_e32 v167, 0xc000, v148
	v_lshl_add_u64 v[222:223], s[0:1], 0, v[140:141]
	v_readfirstlane_b32 s5, v167
	v_add_u32_e32 v129, s61, v145
	v_add_u32_e32 v165, s63, v145
	v_add_u32_e32 v166, s64, v145
	v_lshl_add_u64 v[168:169], v[222:223], 0, s[82:83]
	s_mov_b32 m0, s5
	ds_read_b128 v[186:189], v161
	ds_read_b128 v[190:193], v161 offset:1024
	ds_read_b128 v[194:197], v129
	ds_read_b128 v[198:201], v129 offset:1024
	ds_read_b128 v[202:205], v165
	ds_read_b128 v[206:209], v165 offset:1024
	ds_read_b128 v[210:213], v166
	ds_read_b128 v[214:217], v166 offset:1024
	global_load_lds_dwordx4 v[168:169], off
	v_add_u32_e32 v168, 0xe000, v148
	v_lshl_add_u64 v[238:239], s[0:1], 0, v[142:143]
	v_readfirstlane_b32 s5, v168
	v_lshl_add_u64 v[218:219], v[238:239], 0, s[82:83]
	s_mov_b32 m0, s5
	s_nop 0
	global_load_lds_dwordx4 v[218:219], off
	s_waitcnt lgkmcnt(8)
	s_barrier
	s_waitcnt lgkmcnt(0)
	s_setprio 1
	v_mfma_f32_16x16x32_bf16 v[124:127], v[186:189], v[170:173], v[124:127]
	v_mfma_f32_16x16x32_bf16 v[120:123], v[186:189], v[178:181], v[120:123]
	v_mfma_f32_16x16x32_bf16 v[116:119], v[194:197], v[170:173], v[116:119]
	v_mfma_f32_16x16x32_bf16 v[112:115], v[194:197], v[178:181], v[112:115]
	v_mfma_f32_16x16x32_bf16 v[108:111], v[202:205], v[170:173], v[108:111]
	v_mfma_f32_16x16x32_bf16 v[104:107], v[202:205], v[178:181], v[104:107]
	v_mfma_f32_16x16x32_bf16 v[100:103], v[210:213], v[170:173], v[100:103]
	v_mfma_f32_16x16x32_bf16 v[96:99], v[210:213], v[178:181], v[96:99]
	v_mfma_f32_16x16x32_bf16 v[124:127], v[190:193], v[174:177], v[124:127]
	v_mfma_f32_16x16x32_bf16 v[120:123], v[190:193], v[182:185], v[120:123]
	v_mfma_f32_16x16x32_bf16 v[116:119], v[198:201], v[174:177], v[116:119]
	v_mfma_f32_16x16x32_bf16 v[112:115], v[198:201], v[182:185], v[112:115]
	v_mfma_f32_16x16x32_bf16 v[108:111], v[206:209], v[174:177], v[108:111]
	v_mfma_f32_16x16x32_bf16 v[104:107], v[206:209], v[182:185], v[104:107]
	v_mfma_f32_16x16x32_bf16 v[100:103], v[214:217], v[174:177], v[100:103]
	v_mfma_f32_16x16x32_bf16 v[96:99], v[214:217], v[182:185], v[96:99]
	s_setprio 0
	s_barrier
	v_lshl_add_u64 v[240:241], s[0:1], 0, v[136:137]
	v_readfirstlane_b32 s5, v146
	v_lshl_add_u64 v[242:243], v[240:241], 0, s[84:85]
	s_mov_b32 m0, s5
	ds_read_b128 v[218:221], v162
	ds_read_b128 v[226:229], v162 offset:1024
	ds_read_b128 v[230:233], v162 offset:2048
	ds_read_b128 v[234:237], v162 offset:3072
	global_load_lds_dwordx4 v[242:243], off
	v_lshl_add_u64 v[242:243], s[0:1], 0, v[138:139]
	v_readfirstlane_b32 s5, v147
	v_lshl_add_u64 v[244:245], v[242:243], 0, s[84:85]
	s_mov_b32 m0, s5
	s_nop 0
	global_load_lds_dwordx4 v[244:245], off
	s_barrier
	s_waitcnt lgkmcnt(0)
	s_setprio 1
	v_mfma_f32_16x16x32_bf16 v[92:95], v[186:189], v[218:221], v[92:95]
	v_mfma_f32_16x16x32_bf16 v[88:91], v[186:189], v[230:233], v[88:91]
	v_mfma_f32_16x16x32_bf16 v[84:87], v[194:197], v[218:221], v[84:87]
	v_mfma_f32_16x16x32_bf16 v[80:83], v[194:197], v[230:233], v[80:83]
	v_mfma_f32_16x16x32_bf16 v[76:79], v[202:205], v[218:221], v[76:79]
	v_mfma_f32_16x16x32_bf16 v[72:75], v[202:205], v[230:233], v[72:75]
	v_mfma_f32_16x16x32_bf16 v[68:71], v[210:213], v[218:221], v[68:71]
	v_mfma_f32_16x16x32_bf16 v[64:67], v[210:213], v[230:233], v[64:67]
	v_mfma_f32_16x16x32_bf16 v[92:95], v[190:193], v[226:229], v[92:95]
	v_mfma_f32_16x16x32_bf16 v[88:91], v[190:193], v[234:237], v[88:91]
	v_mfma_f32_16x16x32_bf16 v[84:87], v[198:201], v[226:229], v[84:87]
	v_mfma_f32_16x16x32_bf16 v[80:83], v[198:201], v[234:237], v[80:83]
	v_mfma_f32_16x16x32_bf16 v[76:79], v[206:209], v[226:229], v[76:79]
	v_mfma_f32_16x16x32_bf16 v[72:75], v[206:209], v[234:237], v[72:75]
	v_mfma_f32_16x16x32_bf16 v[68:71], v[214:217], v[226:229], v[68:71]
	v_mfma_f32_16x16x32_bf16 v[64:67], v[214:217], v[234:237], v[64:67]
	s_setprio 0
	v_readfirstlane_b32 s5, v148
	v_lshl_add_u64 v[244:245], v[222:223], 0, s[86:87]
	s_mov_b32 m0, s5
	v_readfirstlane_b32 s5, v149
	s_barrier
	ds_read_b128 v[186:189], v161 offset:16384
	ds_read_b128 v[190:193], v161 offset:17408
	ds_read_b128 v[194:197], v129 offset:16384
	ds_read_b128 v[198:201], v129 offset:17408
	ds_read_b128 v[202:205], v165 offset:16384
	ds_read_b128 v[206:209], v165 offset:17408
	ds_read_b128 v[210:213], v166 offset:16384
	ds_read_b128 v[214:217], v166 offset:17408
	global_load_lds_dwordx4 v[244:245], off
	v_lshl_add_u64 v[244:245], v[238:239], 0, s[86:87]
	s_mov_b32 m0, s5
	s_nop 0
	global_load_lds_dwordx4 v[244:245], off
	s_barrier
	s_waitcnt lgkmcnt(0)
	s_setprio 1
	v_mfma_f32_16x16x32_bf16 v[60:63], v[186:189], v[170:173], v[60:63]
	v_mfma_f32_16x16x32_bf16 v[56:59], v[186:189], v[178:181], v[56:59]
	v_mfma_f32_16x16x32_bf16 v[52:55], v[194:197], v[170:173], v[52:55]
	v_mfma_f32_16x16x32_bf16 v[48:51], v[194:197], v[178:181], v[48:51]
	v_mfma_f32_16x16x32_bf16 v[44:47], v[202:205], v[170:173], v[44:47]
	v_mfma_f32_16x16x32_bf16 v[40:43], v[202:205], v[178:181], v[40:43]
	v_mfma_f32_16x16x32_bf16 v[36:39], v[210:213], v[170:173], v[36:39]
	v_mfma_f32_16x16x32_bf16 v[32:35], v[210:213], v[178:181], v[32:35]
	v_mfma_f32_16x16x32_bf16 v[60:63], v[190:193], v[174:177], v[60:63]
	v_mfma_f32_16x16x32_bf16 v[56:59], v[190:193], v[182:185], v[56:59]
	v_mfma_f32_16x16x32_bf16 v[52:55], v[198:201], v[174:177], v[52:55]
	v_mfma_f32_16x16x32_bf16 v[48:51], v[198:201], v[182:185], v[48:51]
	v_mfma_f32_16x16x32_bf16 v[44:47], v[206:209], v[174:177], v[44:47]
	v_mfma_f32_16x16x32_bf16 v[40:43], v[206:209], v[182:185], v[40:43]
	v_mfma_f32_16x16x32_bf16 v[36:39], v[214:217], v[174:177], v[36:39]
	v_mfma_f32_16x16x32_bf16 v[32:35], v[214:217], v[182:185], v[32:35]
	s_setprio 0
	s_barrier
	v_readfirstlane_b32 s5, v150
	v_lshl_add_u64 v[170:171], v[240:241], 0, s[88:89]
	s_mov_b32 m0, s5
	v_readfirstlane_b32 s5, v151
	global_load_lds_dwordx4 v[170:171], off
	v_lshl_add_u64 v[170:171], v[242:243], 0, s[88:89]
	s_mov_b32 m0, s5
	s_nop 0
	global_load_lds_dwordx4 v[170:171], off
	s_waitcnt vmcnt(6)
	s_barrier
	s_setprio 1
	v_mfma_f32_16x16x32_bf16 v[28:31], v[186:189], v[218:221], v[28:31]
	v_mfma_f32_16x16x32_bf16 v[24:27], v[186:189], v[230:233], v[24:27]
	v_mfma_f32_16x16x32_bf16 v[20:23], v[194:197], v[218:221], v[20:23]
	v_mfma_f32_16x16x32_bf16 v[16:19], v[194:197], v[230:233], v[16:19]
	v_mfma_f32_16x16x32_bf16 v[12:15], v[202:205], v[218:221], v[12:15]
	v_mfma_f32_16x16x32_bf16 v[8:11], v[202:205], v[230:233], v[8:11]
	v_mfma_f32_16x16x32_bf16 v[4:7], v[210:213], v[218:221], v[4:7]
	v_mfma_f32_16x16x32_bf16 v[0:3], v[210:213], v[230:233], v[0:3]
	v_mfma_f32_16x16x32_bf16 v[28:31], v[190:193], v[226:229], v[28:31]
	v_mfma_f32_16x16x32_bf16 v[24:27], v[190:193], v[234:237], v[24:27]
	v_mfma_f32_16x16x32_bf16 v[20:23], v[198:201], v[226:229], v[20:23]
	v_mfma_f32_16x16x32_bf16 v[16:19], v[198:201], v[234:237], v[16:19]
	v_mfma_f32_16x16x32_bf16 v[12:15], v[206:209], v[226:229], v[12:15]
	v_mfma_f32_16x16x32_bf16 v[8:11], v[206:209], v[234:237], v[8:11]
	v_mfma_f32_16x16x32_bf16 v[4:7], v[214:217], v[226:229], v[4:7]
	v_mfma_f32_16x16x32_bf16 v[0:3], v[214:217], v[234:237], v[0:3]
	s_setprio 0
	s_barrier
	ds_read_b128 v[170:173], v163
	ds_read_b128 v[174:177], v163 offset:1024
	ds_read_b128 v[178:181], v163 offset:2048
	ds_read_b128 v[182:185], v163 offset:3072
	v_readfirstlane_b32 s5, v152
	v_lshl_add_u64 v[218:219], v[222:223], 0, s[90:91]
	s_mov_b32 m0, s5
	v_readfirstlane_b32 s5, v153
	ds_read_b128 v[186:189], v161 offset:32768
	ds_read_b128 v[190:193], v161 offset:33792
	ds_read_b128 v[194:197], v129 offset:32768
	ds_read_b128 v[198:201], v129 offset:33792
	ds_read_b128 v[202:205], v165 offset:32768
	ds_read_b128 v[206:209], v165 offset:33792
	ds_read_b128 v[210:213], v166 offset:32768
	ds_read_b128 v[214:217], v166 offset:33792
	global_load_lds_dwordx4 v[218:219], off
	v_lshl_add_u64 v[218:219], v[238:239], 0, s[90:91]
	s_mov_b32 m0, s5
	s_nop 0
	global_load_lds_dwordx4 v[218:219], off
	s_waitcnt lgkmcnt(8)
	s_barrier
	s_waitcnt lgkmcnt(0)
	s_setprio 1
	v_mfma_f32_16x16x32_bf16 v[124:127], v[186:189], v[170:173], v[124:127]
	v_mfma_f32_16x16x32_bf16 v[120:123], v[186:189], v[178:181], v[120:123]
	v_mfma_f32_16x16x32_bf16 v[116:119], v[194:197], v[170:173], v[116:119]
	v_mfma_f32_16x16x32_bf16 v[112:115], v[194:197], v[178:181], v[112:115]
	v_mfma_f32_16x16x32_bf16 v[108:111], v[202:205], v[170:173], v[108:111]
	v_mfma_f32_16x16x32_bf16 v[104:107], v[202:205], v[178:181], v[104:107]
	v_mfma_f32_16x16x32_bf16 v[100:103], v[210:213], v[170:173], v[100:103]
	v_mfma_f32_16x16x32_bf16 v[96:99], v[210:213], v[178:181], v[96:99]
	v_mfma_f32_16x16x32_bf16 v[124:127], v[190:193], v[174:177], v[124:127]
	v_mfma_f32_16x16x32_bf16 v[120:123], v[190:193], v[182:185], v[120:123]
	v_mfma_f32_16x16x32_bf16 v[116:119], v[198:201], v[174:177], v[116:119]
	v_mfma_f32_16x16x32_bf16 v[112:115], v[198:201], v[182:185], v[112:115]
	v_mfma_f32_16x16x32_bf16 v[108:111], v[206:209], v[174:177], v[108:111]
	v_mfma_f32_16x16x32_bf16 v[104:107], v[206:209], v[182:185], v[104:107]
	v_mfma_f32_16x16x32_bf16 v[100:103], v[214:217], v[174:177], v[100:103]
	v_mfma_f32_16x16x32_bf16 v[96:99], v[214:217], v[182:185], v[96:99]
	s_setprio 0
	s_barrier
	v_readfirstlane_b32 s5, v154
	v_lshl_add_u64 v[244:245], v[240:241], 0, s[92:93]
	s_mov_b32 m0, s5
	v_readfirstlane_b32 s5, v155
	ds_read_b128 v[218:221], v164
	ds_read_b128 v[226:229], v164 offset:1024
	ds_read_b128 v[230:233], v164 offset:2048
	ds_read_b128 v[234:237], v164 offset:3072
	global_load_lds_dwordx4 v[244:245], off
	v_lshl_add_u64 v[244:245], v[242:243], 0, s[92:93]
	s_mov_b32 m0, s5
	s_nop 0
	global_load_lds_dwordx4 v[244:245], off
	s_barrier
	s_waitcnt lgkmcnt(0)
	s_setprio 1
	v_mfma_f32_16x16x32_bf16 v[92:95], v[186:189], v[218:221], v[92:95]
	v_mfma_f32_16x16x32_bf16 v[88:91], v[186:189], v[230:233], v[88:91]
	v_mfma_f32_16x16x32_bf16 v[84:87], v[194:197], v[218:221], v[84:87]
	v_mfma_f32_16x16x32_bf16 v[80:83], v[194:197], v[230:233], v[80:83]
	v_mfma_f32_16x16x32_bf16 v[76:79], v[202:205], v[218:221], v[76:79]
	v_mfma_f32_16x16x32_bf16 v[72:75], v[202:205], v[230:233], v[72:75]
	v_mfma_f32_16x16x32_bf16 v[68:71], v[210:213], v[218:221], v[68:71]
	v_mfma_f32_16x16x32_bf16 v[64:67], v[210:213], v[230:233], v[64:67]
	v_mfma_f32_16x16x32_bf16 v[92:95], v[190:193], v[226:229], v[92:95]
	v_mfma_f32_16x16x32_bf16 v[88:91], v[190:193], v[234:237], v[88:91]
	v_mfma_f32_16x16x32_bf16 v[84:87], v[198:201], v[226:229], v[84:87]
	v_mfma_f32_16x16x32_bf16 v[80:83], v[198:201], v[234:237], v[80:83]
	v_mfma_f32_16x16x32_bf16 v[76:79], v[206:209], v[226:229], v[76:79]
	v_mfma_f32_16x16x32_bf16 v[72:75], v[206:209], v[234:237], v[72:75]
	v_mfma_f32_16x16x32_bf16 v[68:71], v[214:217], v[226:229], v[68:71]
	v_mfma_f32_16x16x32_bf16 v[64:67], v[214:217], v[234:237], v[64:67]
	s_setprio 0
	v_readfirstlane_b32 s5, v156
	v_lshl_add_u64 v[222:223], v[222:223], 0, s[94:95]
	s_mov_b32 m0, s5
	v_readfirstlane_b32 s5, v157
	s_barrier
	ds_read_b128 v[186:189], v161 offset:49152
	ds_read_b128 v[190:193], v161 offset:50176
	ds_read_b128 v[194:197], v129 offset:49152
	ds_read_b128 v[198:201], v129 offset:50176
	ds_read_b128 v[202:205], v165 offset:49152
	ds_read_b128 v[206:209], v165 offset:50176
	ds_read_b128 v[210:213], v166 offset:49152
	ds_read_b128 v[214:217], v166 offset:50176
	global_load_lds_dwordx4 v[222:223], off
	v_lshl_add_u64 v[222:223], v[238:239], 0, s[94:95]
	s_mov_b32 m0, s5
	s_nop 0
	global_load_lds_dwordx4 v[222:223], off
	s_barrier
	s_waitcnt lgkmcnt(0)
	s_setprio 1
	v_mfma_f32_16x16x32_bf16 v[60:63], v[186:189], v[170:173], v[60:63]
	v_mfma_f32_16x16x32_bf16 v[56:59], v[186:189], v[178:181], v[56:59]
	v_mfma_f32_16x16x32_bf16 v[52:55], v[194:197], v[170:173], v[52:55]
	v_mfma_f32_16x16x32_bf16 v[48:51], v[194:197], v[178:181], v[48:51]
	v_mfma_f32_16x16x32_bf16 v[44:47], v[202:205], v[170:173], v[44:47]
	v_mfma_f32_16x16x32_bf16 v[40:43], v[202:205], v[178:181], v[40:43]
	v_mfma_f32_16x16x32_bf16 v[36:39], v[210:213], v[170:173], v[36:39]
	v_mfma_f32_16x16x32_bf16 v[32:35], v[210:213], v[178:181], v[32:35]
	v_mfma_f32_16x16x32_bf16 v[60:63], v[190:193], v[174:177], v[60:63]
	v_mfma_f32_16x16x32_bf16 v[56:59], v[190:193], v[182:185], v[56:59]
	v_mfma_f32_16x16x32_bf16 v[52:55], v[198:201], v[174:177], v[52:55]
	v_mfma_f32_16x16x32_bf16 v[48:51], v[198:201], v[182:185], v[48:51]
	v_mfma_f32_16x16x32_bf16 v[44:47], v[206:209], v[174:177], v[44:47]
	v_mfma_f32_16x16x32_bf16 v[40:43], v[206:209], v[182:185], v[40:43]
	v_mfma_f32_16x16x32_bf16 v[36:39], v[214:217], v[174:177], v[36:39]
	v_mfma_f32_16x16x32_bf16 v[32:35], v[214:217], v[182:185], v[32:35]
	s_setprio 0
	s_barrier
	v_readfirstlane_b32 s5, v158
	v_lshl_add_u64 v[170:171], v[240:241], 0, s[96:97]
	s_mov_b32 m0, s5
	v_readfirstlane_b32 s5, v159
	global_load_lds_dwordx4 v[170:171], off
	v_lshl_add_u64 v[170:171], v[242:243], 0, s[96:97]
	s_mov_b32 m0, s5
	s_nop 0
	global_load_lds_dwordx4 v[170:171], off
	s_waitcnt vmcnt(6)
	s_barrier
	s_setprio 1
	v_mfma_f32_16x16x32_bf16 v[28:31], v[186:189], v[218:221], v[28:31]
	v_mfma_f32_16x16x32_bf16 v[24:27], v[186:189], v[230:233], v[24:27]
	v_mfma_f32_16x16x32_bf16 v[20:23], v[194:197], v[218:221], v[20:23]
	v_mfma_f32_16x16x32_bf16 v[16:19], v[194:197], v[230:233], v[16:19]
	v_mfma_f32_16x16x32_bf16 v[12:15], v[202:205], v[218:221], v[12:15]
	v_mfma_f32_16x16x32_bf16 v[8:11], v[202:205], v[230:233], v[8:11]
	v_mfma_f32_16x16x32_bf16 v[4:7], v[210:213], v[218:221], v[4:7]
	v_mfma_f32_16x16x32_bf16 v[0:3], v[210:213], v[230:233], v[0:3]
	v_mfma_f32_16x16x32_bf16 v[28:31], v[190:193], v[226:229], v[28:31]
	v_mfma_f32_16x16x32_bf16 v[24:27], v[190:193], v[234:237], v[24:27]
	v_mfma_f32_16x16x32_bf16 v[20:23], v[198:201], v[226:229], v[20:23]
	v_mfma_f32_16x16x32_bf16 v[16:19], v[198:201], v[234:237], v[16:19]
	v_mfma_f32_16x16x32_bf16 v[12:15], v[206:209], v[226:229], v[12:15]
	v_mfma_f32_16x16x32_bf16 v[8:11], v[206:209], v[234:237], v[8:11]
	v_mfma_f32_16x16x32_bf16 v[4:7], v[214:217], v[226:229], v[4:7]
	v_mfma_f32_16x16x32_bf16 v[0:3], v[214:217], v[234:237], v[0:3]
	s_setprio 0
	s_add_i32 s4, s4, 2
	s_add_u32 s0, s0, 0x100
	s_addc_u32 s1, s1, 0
	s_cmp_lt_u32 s4, 28
	s_barrier
	s_cbranch_scc1 .LBB0_283
	v_readfirstlane_b32 s0, v167
	v_lshl_add_u64 v[134:135], v[134:135], 0, s[34:35]
	s_mov_b32 m0, s0
	v_readfirstlane_b32 s0, v168
	ds_read_b128 v[136:139], v160
	ds_read_b128 v[140:143], v160 offset:1024
	ds_read_b128 v[170:173], v160 offset:2048
	ds_read_b128 v[174:177], v160 offset:3072
	ds_read_b128 v[178:181], v161
	ds_read_b128 v[182:185], v161 offset:1024
	ds_read_b128 v[186:189], v129
	ds_read_b128 v[190:193], v129 offset:1024
	ds_read_b128 v[194:197], v165
	ds_read_b128 v[198:201], v165 offset:1024
	ds_read_b128 v[202:205], v166
	ds_read_b128 v[206:209], v166 offset:1024
	global_load_lds_dwordx4 v[134:135], off
	v_lshl_add_u64 v[132:133], v[132:133], 0, s[34:35]
	s_mov_b32 m0, s0
	s_nop 0
	global_load_lds_dwordx4 v[132:133], off
	s_barrier
	s_waitcnt lgkmcnt(0)
	s_setprio 1
	v_mfma_f32_16x16x32_bf16 v[124:127], v[178:181], v[136:139], v[124:127]
	v_mfma_f32_16x16x32_bf16 v[120:123], v[178:181], v[170:173], v[120:123]
	v_mfma_f32_16x16x32_bf16 v[116:119], v[186:189], v[136:139], v[116:119]
	v_mfma_f32_16x16x32_bf16 v[112:115], v[186:189], v[170:173], v[112:115]
	v_mfma_f32_16x16x32_bf16 v[124:127], v[182:185], v[140:143], v[124:127]
	v_mfma_f32_16x16x32_bf16 v[120:123], v[182:185], v[174:177], v[120:123]
	v_mfma_f32_16x16x32_bf16 v[116:119], v[190:193], v[140:143], v[116:119]
	v_mfma_f32_16x16x32_bf16 v[112:115], v[190:193], v[174:177], v[112:115]
	v_mfma_f32_16x16x32_bf16 v[108:111], v[194:197], v[136:139], v[108:111]
	v_mfma_f32_16x16x32_bf16 v[104:107], v[194:197], v[170:173], v[104:107]
	v_mfma_f32_16x16x32_bf16 v[100:103], v[202:205], v[136:139], v[100:103]
	v_mfma_f32_16x16x32_bf16 v[96:99], v[202:205], v[170:173], v[96:99]
	v_mfma_f32_16x16x32_bf16 v[132:135], v[198:201], v[140:143], v[108:111]
	v_mfma_f32_16x16x32_bf16 v[210:213], v[198:201], v[174:177], v[104:107]
	v_mfma_f32_16x16x32_bf16 v[214:217], v[206:209], v[140:143], v[100:103]
	v_mfma_f32_16x16x32_bf16 v[218:221], v[206:209], v[174:177], v[96:99]
	s_setprio 0
	s_barrier
	s_nop 1
	ds_read_b128 v[96:99], v162
	ds_read_b128 v[100:103], v162 offset:1024
	ds_read_b128 v[104:107], v162 offset:2048
	ds_read_b128 v[108:111], v162 offset:3072
	s_barrier
	s_waitcnt lgkmcnt(0)
	s_setprio 1
	v_mfma_f32_16x16x32_bf16 v[92:95], v[178:181], v[96:99], v[92:95]
	v_mfma_f32_16x16x32_bf16 v[88:91], v[178:181], v[104:107], v[88:91]
	v_mfma_f32_16x16x32_bf16 v[84:87], v[186:189], v[96:99], v[84:87]
	v_mfma_f32_16x16x32_bf16 v[80:83], v[186:189], v[104:107], v[80:83]
	v_mfma_f32_16x16x32_bf16 v[92:95], v[182:185], v[100:103], v[92:95]
	v_mfma_f32_16x16x32_bf16 v[88:91], v[182:185], v[108:111], v[88:91]
	v_mfma_f32_16x16x32_bf16 v[84:87], v[190:193], v[100:103], v[84:87]
	v_mfma_f32_16x16x32_bf16 v[80:83], v[190:193], v[108:111], v[80:83]
	v_mfma_f32_16x16x32_bf16 v[76:79], v[194:197], v[96:99], v[76:79]
	v_mfma_f32_16x16x32_bf16 v[72:75], v[194:197], v[104:107], v[72:75]
	v_mfma_f32_16x16x32_bf16 v[68:71], v[202:205], v[96:99], v[68:71]
	v_mfma_f32_16x16x32_bf16 v[64:67], v[202:205], v[104:107], v[64:67]
	v_mfma_f32_16x16x32_bf16 v[178:181], v[198:201], v[100:103], v[76:79]
	v_mfma_f32_16x16x32_bf16 v[182:185], v[198:201], v[108:111], v[72:75]
	v_mfma_f32_16x16x32_bf16 v[186:189], v[206:209], v[100:103], v[68:71]
	v_mfma_f32_16x16x32_bf16 v[190:193], v[206:209], v[108:111], v[64:67]
	s_setprio 0
	s_barrier
	s_nop 1
	ds_read_b128 v[64:67], v161 offset:16384
	ds_read_b128 v[68:71], v161 offset:17408
	ds_read_b128 v[72:75], v129 offset:16384
	ds_read_b128 v[76:79], v129 offset:17408
	ds_read_b128 v[194:197], v165 offset:16384
	ds_read_b128 v[198:201], v165 offset:17408
	ds_read_b128 v[202:205], v166 offset:16384
	ds_read_b128 v[206:209], v166 offset:17408
	s_waitcnt vmcnt(4)
	s_barrier
	s_waitcnt lgkmcnt(0)
	s_setprio 1
	v_mfma_f32_16x16x32_bf16 v[60:63], v[64:67], v[136:139], v[60:63]
	v_mfma_f32_16x16x32_bf16 v[56:59], v[64:67], v[170:173], v[56:59]
	v_mfma_f32_16x16x32_bf16 v[52:55], v[72:75], v[136:139], v[52:55]
	v_mfma_f32_16x16x32_bf16 v[48:51], v[72:75], v[170:173], v[48:51]
	v_mfma_f32_16x16x32_bf16 v[60:63], v[68:71], v[140:143], v[60:63]
	v_mfma_f32_16x16x32_bf16 v[56:59], v[68:71], v[174:177], v[56:59]
	v_mfma_f32_16x16x32_bf16 v[52:55], v[76:79], v[140:143], v[52:55]
	v_mfma_f32_16x16x32_bf16 v[48:51], v[76:79], v[174:177], v[48:51]
	v_mfma_f32_16x16x32_bf16 v[44:47], v[194:197], v[136:139], v[44:47]
	v_mfma_f32_16x16x32_bf16 v[40:43], v[194:197], v[170:173], v[40:43]
	v_mfma_f32_16x16x32_bf16 v[36:39], v[202:205], v[136:139], v[36:39]
	v_mfma_f32_16x16x32_bf16 v[32:35], v[202:205], v[170:173], v[32:35]
	v_mfma_f32_16x16x32_bf16 v[226:229], v[198:201], v[140:143], v[44:47]
	v_mfma_f32_16x16x32_bf16 v[230:233], v[198:201], v[174:177], v[40:43]
	v_mfma_f32_16x16x32_bf16 v[136:139], v[206:209], v[140:143], v[36:39]
	v_mfma_f32_16x16x32_bf16 v[140:143], v[206:209], v[174:177], v[32:35]
	s_setprio 0
	s_setprio 1
	v_mfma_f32_16x16x32_bf16 v[28:31], v[64:67], v[96:99], v[28:31]
	v_mfma_f32_16x16x32_bf16 v[24:27], v[64:67], v[104:107], v[24:27]
	v_mfma_f32_16x16x32_bf16 v[20:23], v[72:75], v[96:99], v[20:23]
	v_mfma_f32_16x16x32_bf16 v[16:19], v[72:75], v[104:107], v[16:19]
	v_mfma_f32_16x16x32_bf16 v[28:31], v[68:71], v[100:103], v[28:31]
	v_mfma_f32_16x16x32_bf16 v[24:27], v[68:71], v[108:111], v[24:27]
	v_mfma_f32_16x16x32_bf16 v[20:23], v[76:79], v[100:103], v[20:23]
	v_mfma_f32_16x16x32_bf16 v[16:19], v[76:79], v[108:111], v[16:19]
	v_mfma_f32_16x16x32_bf16 v[12:15], v[194:197], v[96:99], v[12:15]
	v_mfma_f32_16x16x32_bf16 v[8:11], v[194:197], v[104:107], v[8:11]
	v_mfma_f32_16x16x32_bf16 v[4:7], v[202:205], v[96:99], v[4:7]
	v_mfma_f32_16x16x32_bf16 v[0:3], v[202:205], v[104:107], v[0:3]
	v_mfma_f32_16x16x32_bf16 v[168:171], v[198:201], v[100:103], v[12:15]
	v_mfma_f32_16x16x32_bf16 v[172:175], v[198:201], v[108:111], v[8:11]
	v_mfma_f32_16x16x32_bf16 v[194:197], v[206:209], v[100:103], v[4:7]
	v_mfma_f32_16x16x32_bf16 v[198:201], v[206:209], v[108:111], v[0:3]
	s_setprio 0
	s_barrier
	s_nop 1
	ds_read_b128 v[0:3], v163
	ds_read_b128 v[4:7], v163 offset:1024
	ds_read_b128 v[202:205], v163 offset:2048
	ds_read_b128 v[206:209], v163 offset:3072
	ds_read_b128 v[8:11], v161 offset:32768
	ds_read_b128 v[12:15], v161 offset:33792
	ds_read_b128 v[32:35], v129 offset:32768
	ds_read_b128 v[36:39], v129 offset:33792
	ds_read_b128 v[40:43], v165 offset:32768
	ds_read_b128 v[44:47], v165 offset:33792
	ds_read_b128 v[234:237], v166 offset:32768
	ds_read_b128 v[238:241], v166 offset:33792
	s_waitcnt vmcnt(2)
	s_barrier
	s_waitcnt lgkmcnt(0)
	s_setprio 1
	v_mfma_f32_16x16x32_bf16 v[64:67], v[8:11], v[0:3], v[124:127]
	v_mfma_f32_16x16x32_bf16 v[104:107], v[12:15], v[4:7], v[64:67]
	v_mfma_f32_16x16x32_bf16 v[64:67], v[8:11], v[202:205], v[120:123]
	v_mfma_f32_16x16x32_bf16 v[108:111], v[12:15], v[206:209], v[64:67]
	v_mfma_f32_16x16x32_bf16 v[64:67], v[32:35], v[0:3], v[116:119]
	v_mfma_f32_16x16x32_bf16 v[96:99], v[36:39], v[4:7], v[64:67]
	v_mfma_f32_16x16x32_bf16 v[64:67], v[32:35], v[202:205], v[112:115]
	v_mfma_f32_16x16x32_bf16 v[100:103], v[36:39], v[206:209], v[64:67]
	v_mfma_f32_16x16x32_bf16 v[64:67], v[40:43], v[0:3], v[132:135]
	v_mfma_f32_16x16x32_bf16 v[72:75], v[44:47], v[4:7], v[64:67]
	v_mfma_f32_16x16x32_bf16 v[64:67], v[40:43], v[202:205], v[210:213]
	v_mfma_f32_16x16x32_bf16 v[76:79], v[44:47], v[206:209], v[64:67]
	v_mfma_f32_16x16x32_bf16 v[64:67], v[234:237], v[0:3], v[214:217]
	v_mfma_f32_16x16x32_bf16 v[68:71], v[234:237], v[202:205], v[218:221]
	v_mfma_f32_16x16x32_bf16 v[64:67], v[238:241], v[4:7], v[64:67]
	v_mfma_f32_16x16x32_bf16 v[68:71], v[238:241], v[206:209], v[68:71]
	s_setprio 0
	s_barrier
	ds_read_b128 v[132:135], v164
	ds_read_b128 v[210:213], v164 offset:1024
	ds_read_b128 v[214:217], v164 offset:2048
	ds_read_b128 v[218:221], v164 offset:3072
	s_waitcnt vmcnt(0)
	s_barrier
	s_waitcnt lgkmcnt(0)
	s_setprio 1
	v_mfma_f32_16x16x32_bf16 v[92:95], v[8:11], v[132:135], v[92:95]
	v_mfma_f32_16x16x32_bf16 v[8:11], v[8:11], v[214:217], v[88:91]
	v_mfma_f32_16x16x32_bf16 v[124:127], v[12:15], v[218:221], v[8:11]
	v_mfma_f32_16x16x32_bf16 v[8:11], v[32:35], v[132:135], v[84:87]
	v_mfma_f32_16x16x32_bf16 v[112:115], v[36:39], v[210:213], v[8:11]
	v_mfma_f32_16x16x32_bf16 v[8:11], v[32:35], v[214:217], v[80:83]
	v_mfma_f32_16x16x32_bf16 v[116:119], v[36:39], v[218:221], v[8:11]
	v_mfma_f32_16x16x32_bf16 v[8:11], v[40:43], v[132:135], v[178:181]
	v_mfma_f32_16x16x32_bf16 v[88:91], v[44:47], v[210:213], v[8:11]
	v_mfma_f32_16x16x32_bf16 v[8:11], v[40:43], v[214:217], v[182:185]
	v_mfma_f32_16x16x32_bf16 v[120:123], v[12:15], v[210:213], v[92:95]
	v_mfma_f32_16x16x32_bf16 v[92:95], v[44:47], v[218:221], v[8:11]
	v_mfma_f32_16x16x32_bf16 v[8:11], v[234:237], v[132:135], v[186:189]
	v_mfma_f32_16x16x32_bf16 v[80:83], v[238:241], v[210:213], v[8:11]
	v_mfma_f32_16x16x32_bf16 v[8:11], v[234:237], v[214:217], v[190:193]
	v_mfma_f32_16x16x32_bf16 v[84:87], v[238:241], v[218:221], v[8:11]
	s_setprio 0
	s_barrier
	ds_read_b128 v[176:179], v161 offset:49152
	ds_read_b128 v[180:183], v161 offset:50176
	ds_read_b128 v[184:187], v129 offset:49152
	ds_read_b128 v[188:191], v129 offset:50176
	ds_read_b128 v[234:237], v165 offset:49152
	ds_read_b128 v[238:241], v165 offset:50176
	ds_read_b128 v[242:245], v166 offset:49152
	ds_read_b128 v[246:249], v166 offset:50176
	s_barrier
	s_waitcnt lgkmcnt(0)
	s_setprio 1
	v_mfma_f32_16x16x32_bf16 v[8:11], v[176:179], v[0:3], v[60:63]
	v_mfma_f32_16x16x32_bf16 v[40:43], v[180:183], v[4:7], v[8:11]
	v_mfma_f32_16x16x32_bf16 v[8:11], v[176:179], v[202:205], v[56:59]
	v_mfma_f32_16x16x32_bf16 v[44:47], v[180:183], v[206:209], v[8:11]
	v_mfma_f32_16x16x32_bf16 v[8:11], v[184:187], v[0:3], v[52:55]
	v_mfma_f32_16x16x32_bf16 v[32:35], v[188:191], v[4:7], v[8:11]
	v_mfma_f32_16x16x32_bf16 v[8:11], v[184:187], v[202:205], v[48:51]
	v_mfma_f32_16x16x32_bf16 v[36:39], v[188:191], v[206:209], v[8:11]
	v_mfma_f32_16x16x32_bf16 v[8:11], v[234:237], v[0:3], v[226:229]
	v_mfma_f32_16x16x32_bf16 v[0:3], v[242:245], v[0:3], v[136:139]
	v_mfma_f32_16x16x32_bf16 v[8:11], v[238:241], v[4:7], v[8:11]
	v_mfma_f32_16x16x32_bf16 v[12:15], v[234:237], v[202:205], v[230:233]
	v_mfma_f32_16x16x32_bf16 v[0:3], v[246:249], v[4:7], v[0:3]
	v_mfma_f32_16x16x32_bf16 v[4:7], v[242:245], v[202:205], v[140:143]
	v_mfma_f32_16x16x32_bf16 v[12:15], v[238:241], v[206:209], v[12:15]
	v_mfma_f32_16x16x32_bf16 v[4:7], v[246:249], v[206:209], v[4:7]
	s_setprio 0
	s_setprio 1
	v_mfma_f32_16x16x32_bf16 v[16:19], v[184:187], v[214:217], v[16:19]
	v_mfma_f32_16x16x32_bf16 v[24:27], v[176:179], v[214:217], v[24:27]
	v_mfma_f32_16x16x32_bf16 v[52:55], v[188:191], v[218:221], v[16:19]
	v_mfma_f32_16x16x32_bf16 v[16:19], v[234:237], v[132:135], v[168:171]
	v_mfma_f32_16x16x32_bf16 v[28:31], v[176:179], v[132:135], v[28:31]
	v_mfma_f32_16x16x32_bf16 v[60:63], v[180:183], v[218:221], v[24:27]
	v_mfma_f32_16x16x32_bf16 v[20:23], v[184:187], v[132:135], v[20:23]
	v_mfma_f32_16x16x32_bf16 v[24:27], v[238:241], v[210:213], v[16:19]
	v_mfma_f32_16x16x32_bf16 v[16:19], v[234:237], v[214:217], v[172:175]
	v_mfma_f32_16x16x32_bf16 v[56:59], v[180:183], v[210:213], v[28:31]
	v_mfma_f32_16x16x32_bf16 v[48:51], v[188:191], v[210:213], v[20:23]
	v_mfma_f32_16x16x32_bf16 v[28:31], v[238:241], v[218:221], v[16:19]
	v_mfma_f32_16x16x32_bf16 v[16:19], v[242:245], v[132:135], v[194:197]
	v_mfma_f32_16x16x32_bf16 v[20:23], v[242:245], v[214:217], v[198:201]
	v_mfma_f32_16x16x32_bf16 v[16:19], v[246:249], v[210:213], v[16:19]
	v_mfma_f32_16x16x32_bf16 v[20:23], v[246:249], v[218:221], v[20:23]
	s_setprio 0
	s_andn2_b64 vcc, exec, s[40:41]
	s_barrier
	s_cbranch_vccnz .LBB0_286
	s_barrier

.LBB0_921:
	ds_read_b128 v[170:173], v162
	ds_read_b128 v[174:177], v162 offset:1024
	ds_read_b128 v[178:181], v162 offset:2048
	ds_read_b128 v[182:185], v162 offset:3072
	v_add_u32_e32 v167, 0xc000, v150
	v_lshl_add_u64 v[222:223], s[22:23], 0, v[142:143]
	v_readfirstlane_b32 s19, v167
	v_add_u32_e32 v129, s60, v147
	v_add_u32_e32 v131, s62, v147
	v_add_u32_e32 v132, s63, v147
	v_lshl_add_u64 v[168:169], v[222:223], 0, s[10:11]
	s_mov_b32 m0, s19
	ds_read_b128 v[186:189], v163
	ds_read_b128 v[190:193], v163 offset:1024
	ds_read_b128 v[194:197], v129
	ds_read_b128 v[198:201], v129 offset:1024
	ds_read_b128 v[202:205], v131
	ds_read_b128 v[206:209], v131 offset:1024
	ds_read_b128 v[210:213], v132
	ds_read_b128 v[214:217], v132 offset:1024
	global_load_lds_dwordx4 v[168:169], off
	v_add_u32_e32 v168, 0xe000, v150
	v_lshl_add_u64 v[238:239], s[22:23], 0, v[144:145]
	v_readfirstlane_b32 s19, v168
	v_lshl_add_u64 v[218:219], v[238:239], 0, s[10:11]
	s_mov_b32 m0, s19
	s_nop 0
	global_load_lds_dwordx4 v[218:219], off
	s_waitcnt lgkmcnt(8)
	s_barrier
	s_waitcnt lgkmcnt(0)
	s_setprio 1
	v_mfma_f32_16x16x32_bf16 v[124:127], v[186:189], v[170:173], v[124:127]
	v_mfma_f32_16x16x32_bf16 v[120:123], v[186:189], v[178:181], v[120:123]
	v_mfma_f32_16x16x32_bf16 v[116:119], v[194:197], v[170:173], v[116:119]
	v_mfma_f32_16x16x32_bf16 v[112:115], v[194:197], v[178:181], v[112:115]
	v_mfma_f32_16x16x32_bf16 v[108:111], v[202:205], v[170:173], v[108:111]
	v_mfma_f32_16x16x32_bf16 v[104:107], v[202:205], v[178:181], v[104:107]
	v_mfma_f32_16x16x32_bf16 v[100:103], v[210:213], v[170:173], v[100:103]
	v_mfma_f32_16x16x32_bf16 v[96:99], v[210:213], v[178:181], v[96:99]
	v_mfma_f32_16x16x32_bf16 v[124:127], v[190:193], v[174:177], v[124:127]
	v_mfma_f32_16x16x32_bf16 v[120:123], v[190:193], v[182:185], v[120:123]
	v_mfma_f32_16x16x32_bf16 v[116:119], v[198:201], v[174:177], v[116:119]
	v_mfma_f32_16x16x32_bf16 v[112:115], v[198:201], v[182:185], v[112:115]
	v_mfma_f32_16x16x32_bf16 v[108:111], v[206:209], v[174:177], v[108:111]
	v_mfma_f32_16x16x32_bf16 v[104:107], v[206:209], v[182:185], v[104:107]
	v_mfma_f32_16x16x32_bf16 v[100:103], v[214:217], v[174:177], v[100:103]
	v_mfma_f32_16x16x32_bf16 v[96:99], v[214:217], v[182:185], v[96:99]
	s_setprio 0
	s_barrier
	v_lshl_add_u64 v[240:241], s[22:23], 0, v[138:139]
	v_readfirstlane_b32 s19, v148
	v_lshl_add_u64 v[242:243], v[240:241], 0, s[12:13]
	s_mov_b32 m0, s19
	ds_read_b128 v[218:221], v164
	ds_read_b128 v[226:229], v164 offset:1024
	ds_read_b128 v[230:233], v164 offset:2048
	ds_read_b128 v[234:237], v164 offset:3072
	global_load_lds_dwordx4 v[242:243], off
	v_lshl_add_u64 v[242:243], s[22:23], 0, v[140:141]
	v_readfirstlane_b32 s19, v149
	v_lshl_add_u64 v[244:245], v[242:243], 0, s[12:13]
	s_mov_b32 m0, s19
	s_nop 0
	global_load_lds_dwordx4 v[244:245], off
	s_barrier
	s_waitcnt lgkmcnt(0)
	s_setprio 1
	v_mfma_f32_16x16x32_bf16 v[92:95], v[186:189], v[218:221], v[92:95]
	v_mfma_f32_16x16x32_bf16 v[88:91], v[186:189], v[230:233], v[88:91]
	v_mfma_f32_16x16x32_bf16 v[84:87], v[194:197], v[218:221], v[84:87]
	v_mfma_f32_16x16x32_bf16 v[80:83], v[194:197], v[230:233], v[80:83]
	v_mfma_f32_16x16x32_bf16 v[76:79], v[202:205], v[218:221], v[76:79]
	v_mfma_f32_16x16x32_bf16 v[72:75], v[202:205], v[230:233], v[72:75]
	v_mfma_f32_16x16x32_bf16 v[68:71], v[210:213], v[218:221], v[68:71]
	v_mfma_f32_16x16x32_bf16 v[64:67], v[210:213], v[230:233], v[64:67]
	v_mfma_f32_16x16x32_bf16 v[92:95], v[190:193], v[226:229], v[92:95]
	v_mfma_f32_16x16x32_bf16 v[88:91], v[190:193], v[234:237], v[88:91]
	v_mfma_f32_16x16x32_bf16 v[84:87], v[198:201], v[226:229], v[84:87]
	v_mfma_f32_16x16x32_bf16 v[80:83], v[198:201], v[234:237], v[80:83]
	v_mfma_f32_16x16x32_bf16 v[76:79], v[206:209], v[226:229], v[76:79]
	v_mfma_f32_16x16x32_bf16 v[72:75], v[206:209], v[234:237], v[72:75]
	v_mfma_f32_16x16x32_bf16 v[68:71], v[214:217], v[226:229], v[68:71]
	v_mfma_f32_16x16x32_bf16 v[64:67], v[214:217], v[234:237], v[64:67]
	s_setprio 0
	v_readfirstlane_b32 s19, v150
	v_lshl_add_u64 v[244:245], v[222:223], 0, s[14:15]
	s_mov_b32 m0, s19
	v_readfirstlane_b32 s19, v151
	s_barrier
	ds_read_b128 v[186:189], v163 offset:16384
	ds_read_b128 v[190:193], v163 offset:17408
	ds_read_b128 v[194:197], v129 offset:16384
	ds_read_b128 v[198:201], v129 offset:17408
	ds_read_b128 v[202:205], v131 offset:16384
	ds_read_b128 v[206:209], v131 offset:17408
	ds_read_b128 v[210:213], v132 offset:16384
	ds_read_b128 v[214:217], v132 offset:17408
	global_load_lds_dwordx4 v[244:245], off
	v_lshl_add_u64 v[244:245], v[238:239], 0, s[14:15]
	s_mov_b32 m0, s19
	s_nop 0
	global_load_lds_dwordx4 v[244:245], off
	s_barrier
	s_waitcnt lgkmcnt(0)
	s_setprio 1
	v_mfma_f32_16x16x32_bf16 v[60:63], v[186:189], v[170:173], v[60:63]
	v_mfma_f32_16x16x32_bf16 v[56:59], v[186:189], v[178:181], v[56:59]
	v_mfma_f32_16x16x32_bf16 v[52:55], v[194:197], v[170:173], v[52:55]
	v_mfma_f32_16x16x32_bf16 v[48:51], v[194:197], v[178:181], v[48:51]
	v_mfma_f32_16x16x32_bf16 v[44:47], v[202:205], v[170:173], v[44:47]
	v_mfma_f32_16x16x32_bf16 v[40:43], v[202:205], v[178:181], v[40:43]
	v_mfma_f32_16x16x32_bf16 v[36:39], v[210:213], v[170:173], v[36:39]
	v_mfma_f32_16x16x32_bf16 v[32:35], v[210:213], v[178:181], v[32:35]
	v_mfma_f32_16x16x32_bf16 v[60:63], v[190:193], v[174:177], v[60:63]
	v_mfma_f32_16x16x32_bf16 v[56:59], v[190:193], v[182:185], v[56:59]
	v_mfma_f32_16x16x32_bf16 v[52:55], v[198:201], v[174:177], v[52:55]
	v_mfma_f32_16x16x32_bf16 v[48:51], v[198:201], v[182:185], v[48:51]
	v_mfma_f32_16x16x32_bf16 v[44:47], v[206:209], v[174:177], v[44:47]
	v_mfma_f32_16x16x32_bf16 v[40:43], v[206:209], v[182:185], v[40:43]
	v_mfma_f32_16x16x32_bf16 v[36:39], v[214:217], v[174:177], v[36:39]
	v_mfma_f32_16x16x32_bf16 v[32:35], v[214:217], v[182:185], v[32:35]
	s_setprio 0
	s_barrier
	v_readfirstlane_b32 s19, v152
	v_lshl_add_u64 v[170:171], v[240:241], 0, s[16:17]
	s_mov_b32 m0, s19
	v_readfirstlane_b32 s19, v153
	global_load_lds_dwordx4 v[170:171], off
	v_lshl_add_u64 v[170:171], v[242:243], 0, s[16:17]
	s_mov_b32 m0, s19
	s_nop 0
	global_load_lds_dwordx4 v[170:171], off
	s_waitcnt vmcnt(6)
	s_barrier
	s_setprio 1
	v_mfma_f32_16x16x32_bf16 v[28:31], v[186:189], v[218:221], v[28:31]
	v_mfma_f32_16x16x32_bf16 v[24:27], v[186:189], v[230:233], v[24:27]
	v_mfma_f32_16x16x32_bf16 v[20:23], v[194:197], v[218:221], v[20:23]
	v_mfma_f32_16x16x32_bf16 v[16:19], v[194:197], v[230:233], v[16:19]
	v_mfma_f32_16x16x32_bf16 v[12:15], v[202:205], v[218:221], v[12:15]
	v_mfma_f32_16x16x32_bf16 v[8:11], v[202:205], v[230:233], v[8:11]
	v_mfma_f32_16x16x32_bf16 v[4:7], v[210:213], v[218:221], v[4:7]
	v_mfma_f32_16x16x32_bf16 v[0:3], v[210:213], v[230:233], v[0:3]
	v_mfma_f32_16x16x32_bf16 v[28:31], v[190:193], v[226:229], v[28:31]
	v_mfma_f32_16x16x32_bf16 v[24:27], v[190:193], v[234:237], v[24:27]
	v_mfma_f32_16x16x32_bf16 v[20:23], v[198:201], v[226:229], v[20:23]
	v_mfma_f32_16x16x32_bf16 v[16:19], v[198:201], v[234:237], v[16:19]
	v_mfma_f32_16x16x32_bf16 v[12:15], v[206:209], v[226:229], v[12:15]
	v_mfma_f32_16x16x32_bf16 v[8:11], v[206:209], v[234:237], v[8:11]
	v_mfma_f32_16x16x32_bf16 v[4:7], v[214:217], v[226:229], v[4:7]
	v_mfma_f32_16x16x32_bf16 v[0:3], v[214:217], v[234:237], v[0:3]
	s_setprio 0
	s_barrier
	ds_read_b128 v[170:173], v165
	ds_read_b128 v[174:177], v165 offset:1024
	ds_read_b128 v[178:181], v165 offset:2048
	ds_read_b128 v[182:185], v165 offset:3072
	v_readfirstlane_b32 s19, v154
	v_lshl_add_u64 v[218:219], v[222:223], 0, s[34:35]
	s_mov_b32 m0, s19
	v_readfirstlane_b32 s19, v155
	ds_read_b128 v[186:189], v163 offset:32768
	ds_read_b128 v[190:193], v163 offset:33792
	ds_read_b128 v[194:197], v129 offset:32768
	ds_read_b128 v[198:201], v129 offset:33792
	ds_read_b128 v[202:205], v131 offset:32768
	ds_read_b128 v[206:209], v131 offset:33792
	ds_read_b128 v[210:213], v132 offset:32768
	ds_read_b128 v[214:217], v132 offset:33792
	global_load_lds_dwordx4 v[218:219], off
	v_lshl_add_u64 v[218:219], v[238:239], 0, s[34:35]
	s_mov_b32 m0, s19
	s_nop 0
	global_load_lds_dwordx4 v[218:219], off
	s_waitcnt lgkmcnt(8)
	s_barrier
	s_waitcnt lgkmcnt(0)
	s_setprio 1
	v_mfma_f32_16x16x32_bf16 v[124:127], v[186:189], v[170:173], v[124:127]
	v_mfma_f32_16x16x32_bf16 v[120:123], v[186:189], v[178:181], v[120:123]
	v_mfma_f32_16x16x32_bf16 v[116:119], v[194:197], v[170:173], v[116:119]
	v_mfma_f32_16x16x32_bf16 v[112:115], v[194:197], v[178:181], v[112:115]
	v_mfma_f32_16x16x32_bf16 v[108:111], v[202:205], v[170:173], v[108:111]
	v_mfma_f32_16x16x32_bf16 v[104:107], v[202:205], v[178:181], v[104:107]
	v_mfma_f32_16x16x32_bf16 v[100:103], v[210:213], v[170:173], v[100:103]
	v_mfma_f32_16x16x32_bf16 v[96:99], v[210:213], v[178:181], v[96:99]
	v_mfma_f32_16x16x32_bf16 v[124:127], v[190:193], v[174:177], v[124:127]
	v_mfma_f32_16x16x32_bf16 v[120:123], v[190:193], v[182:185], v[120:123]
	v_mfma_f32_16x16x32_bf16 v[116:119], v[198:201], v[174:177], v[116:119]
	v_mfma_f32_16x16x32_bf16 v[112:115], v[198:201], v[182:185], v[112:115]
	v_mfma_f32_16x16x32_bf16 v[108:111], v[206:209], v[174:177], v[108:111]
	v_mfma_f32_16x16x32_bf16 v[104:107], v[206:209], v[182:185], v[104:107]
	v_mfma_f32_16x16x32_bf16 v[100:103], v[214:217], v[174:177], v[100:103]
	v_mfma_f32_16x16x32_bf16 v[96:99], v[214:217], v[182:185], v[96:99]
	s_setprio 0
	s_barrier
	v_readfirstlane_b32 s19, v156
	v_lshl_add_u64 v[244:245], v[240:241], 0, s[36:37]
	s_mov_b32 m0, s19
	v_readfirstlane_b32 s19, v157
	ds_read_b128 v[218:221], v166
	ds_read_b128 v[226:229], v166 offset:1024
	ds_read_b128 v[230:233], v166 offset:2048
	ds_read_b128 v[234:237], v166 offset:3072
	global_load_lds_dwordx4 v[244:245], off
	v_lshl_add_u64 v[244:245], v[242:243], 0, s[36:37]
	s_mov_b32 m0, s19
	s_nop 0
	global_load_lds_dwordx4 v[244:245], off
	s_barrier
	s_waitcnt lgkmcnt(0)
	s_setprio 1
	v_mfma_f32_16x16x32_bf16 v[92:95], v[186:189], v[218:221], v[92:95]
	v_mfma_f32_16x16x32_bf16 v[88:91], v[186:189], v[230:233], v[88:91]
	v_mfma_f32_16x16x32_bf16 v[84:87], v[194:197], v[218:221], v[84:87]
	v_mfma_f32_16x16x32_bf16 v[80:83], v[194:197], v[230:233], v[80:83]
	v_mfma_f32_16x16x32_bf16 v[76:79], v[202:205], v[218:221], v[76:79]
	v_mfma_f32_16x16x32_bf16 v[72:75], v[202:205], v[230:233], v[72:75]
	v_mfma_f32_16x16x32_bf16 v[68:71], v[210:213], v[218:221], v[68:71]
	v_mfma_f32_16x16x32_bf16 v[64:67], v[210:213], v[230:233], v[64:67]
	v_mfma_f32_16x16x32_bf16 v[92:95], v[190:193], v[226:229], v[92:95]
	v_mfma_f32_16x16x32_bf16 v[88:91], v[190:193], v[234:237], v[88:91]
	v_mfma_f32_16x16x32_bf16 v[84:87], v[198:201], v[226:229], v[84:87]
	v_mfma_f32_16x16x32_bf16 v[80:83], v[198:201], v[234:237], v[80:83]
	v_mfma_f32_16x16x32_bf16 v[76:79], v[206:209], v[226:229], v[76:79]
	v_mfma_f32_16x16x32_bf16 v[72:75], v[206:209], v[234:237], v[72:75]
	v_mfma_f32_16x16x32_bf16 v[68:71], v[214:217], v[226:229], v[68:71]
	v_mfma_f32_16x16x32_bf16 v[64:67], v[214:217], v[234:237], v[64:67]
	s_setprio 0
	v_readfirstlane_b32 s19, v158
	v_lshl_add_u64 v[222:223], v[222:223], 0, s[38:39]
	s_mov_b32 m0, s19
	v_readfirstlane_b32 s19, v159
	s_barrier
	ds_read_b128 v[186:189], v163 offset:49152
	ds_read_b128 v[190:193], v163 offset:50176
	ds_read_b128 v[194:197], v129 offset:49152
	ds_read_b128 v[198:201], v129 offset:50176
	ds_read_b128 v[202:205], v131 offset:49152
	ds_read_b128 v[206:209], v131 offset:50176
	ds_read_b128 v[210:213], v132 offset:49152
	ds_read_b128 v[214:217], v132 offset:50176
	global_load_lds_dwordx4 v[222:223], off
	v_lshl_add_u64 v[222:223], v[238:239], 0, s[38:39]
	s_mov_b32 m0, s19
	s_nop 0
	global_load_lds_dwordx4 v[222:223], off
	s_barrier
	s_waitcnt lgkmcnt(0)
	s_setprio 1
	v_mfma_f32_16x16x32_bf16 v[60:63], v[186:189], v[170:173], v[60:63]
	v_mfma_f32_16x16x32_bf16 v[56:59], v[186:189], v[178:181], v[56:59]
	v_mfma_f32_16x16x32_bf16 v[52:55], v[194:197], v[170:173], v[52:55]
	v_mfma_f32_16x16x32_bf16 v[48:51], v[194:197], v[178:181], v[48:51]
	v_mfma_f32_16x16x32_bf16 v[44:47], v[202:205], v[170:173], v[44:47]
	v_mfma_f32_16x16x32_bf16 v[40:43], v[202:205], v[178:181], v[40:43]
	v_mfma_f32_16x16x32_bf16 v[36:39], v[210:213], v[170:173], v[36:39]
	v_mfma_f32_16x16x32_bf16 v[32:35], v[210:213], v[178:181], v[32:35]
	v_mfma_f32_16x16x32_bf16 v[60:63], v[190:193], v[174:177], v[60:63]
	v_mfma_f32_16x16x32_bf16 v[56:59], v[190:193], v[182:185], v[56:59]
	v_mfma_f32_16x16x32_bf16 v[52:55], v[198:201], v[174:177], v[52:55]
	v_mfma_f32_16x16x32_bf16 v[48:51], v[198:201], v[182:185], v[48:51]
	v_mfma_f32_16x16x32_bf16 v[44:47], v[206:209], v[174:177], v[44:47]
	v_mfma_f32_16x16x32_bf16 v[40:43], v[206:209], v[182:185], v[40:43]
	v_mfma_f32_16x16x32_bf16 v[36:39], v[214:217], v[174:177], v[36:39]
	v_mfma_f32_16x16x32_bf16 v[32:35], v[214:217], v[182:185], v[32:35]
	s_setprio 0
	s_barrier
	v_readfirstlane_b32 s19, v160
	v_lshl_add_u64 v[170:171], v[240:241], 0, s[40:41]
	s_mov_b32 m0, s19
	v_readfirstlane_b32 s19, v161
	global_load_lds_dwordx4 v[170:171], off
	v_lshl_add_u64 v[170:171], v[242:243], 0, s[40:41]
	s_mov_b32 m0, s19
	s_nop 0
	global_load_lds_dwordx4 v[170:171], off
	s_waitcnt vmcnt(6)
	s_barrier
	s_setprio 1
	v_mfma_f32_16x16x32_bf16 v[28:31], v[186:189], v[218:221], v[28:31]
	v_mfma_f32_16x16x32_bf16 v[24:27], v[186:189], v[230:233], v[24:27]
	v_mfma_f32_16x16x32_bf16 v[20:23], v[194:197], v[218:221], v[20:23]
	v_mfma_f32_16x16x32_bf16 v[16:19], v[194:197], v[230:233], v[16:19]
	v_mfma_f32_16x16x32_bf16 v[12:15], v[202:205], v[218:221], v[12:15]
	v_mfma_f32_16x16x32_bf16 v[8:11], v[202:205], v[230:233], v[8:11]
	v_mfma_f32_16x16x32_bf16 v[4:7], v[210:213], v[218:221], v[4:7]
	v_mfma_f32_16x16x32_bf16 v[0:3], v[210:213], v[230:233], v[0:3]
	v_mfma_f32_16x16x32_bf16 v[28:31], v[190:193], v[226:229], v[28:31]
	v_mfma_f32_16x16x32_bf16 v[24:27], v[190:193], v[234:237], v[24:27]
	v_mfma_f32_16x16x32_bf16 v[20:23], v[198:201], v[226:229], v[20:23]
	v_mfma_f32_16x16x32_bf16 v[16:19], v[198:201], v[234:237], v[16:19]
	v_mfma_f32_16x16x32_bf16 v[12:15], v[206:209], v[226:229], v[12:15]
	v_mfma_f32_16x16x32_bf16 v[8:11], v[206:209], v[234:237], v[8:11]
	v_mfma_f32_16x16x32_bf16 v[4:7], v[214:217], v[226:229], v[4:7]
	v_mfma_f32_16x16x32_bf16 v[0:3], v[214:217], v[234:237], v[0:3]
	s_setprio 0
	s_add_i32 s18, s18, 2
	s_add_u32 s22, s22, 0x100
	s_addc_u32 s23, s23, 0
	s_cmp_lt_u32 s18, 28
	s_barrier
	s_cbranch_scc1 .LBB0_921
	v_readfirstlane_b32 s18, v167
	v_lshl_add_u64 v[136:137], v[136:137], 0, s[44:45]
	s_mov_b32 m0, s18
	v_readfirstlane_b32 s18, v168
	ds_read_b128 v[138:141], v162
	ds_read_b128 v[142:145], v162 offset:1024
	ds_read_b128 v[170:173], v162 offset:2048
	ds_read_b128 v[174:177], v162 offset:3072
	ds_read_b128 v[178:181], v163
	ds_read_b128 v[182:185], v163 offset:1024
	ds_read_b128 v[186:189], v129
	ds_read_b128 v[190:193], v129 offset:1024
	ds_read_b128 v[194:197], v131
	ds_read_b128 v[198:201], v131 offset:1024
	ds_read_b128 v[202:205], v132
	ds_read_b128 v[206:209], v132 offset:1024
	global_load_lds_dwordx4 v[136:137], off
	v_lshl_add_u64 v[134:135], v[134:135], 0, s[44:45]
	s_mov_b32 m0, s18
	s_nop 0
	global_load_lds_dwordx4 v[134:135], off
	s_barrier
	s_waitcnt lgkmcnt(0)
	s_setprio 1
	v_mfma_f32_16x16x32_bf16 v[124:127], v[178:181], v[138:141], v[124:127]
	v_mfma_f32_16x16x32_bf16 v[120:123], v[178:181], v[170:173], v[120:123]
	v_mfma_f32_16x16x32_bf16 v[116:119], v[186:189], v[138:141], v[116:119]
	v_mfma_f32_16x16x32_bf16 v[112:115], v[186:189], v[170:173], v[112:115]
	v_mfma_f32_16x16x32_bf16 v[124:127], v[182:185], v[142:145], v[124:127]
	v_mfma_f32_16x16x32_bf16 v[120:123], v[182:185], v[174:177], v[120:123]
	v_mfma_f32_16x16x32_bf16 v[116:119], v[190:193], v[142:145], v[116:119]
	v_mfma_f32_16x16x32_bf16 v[112:115], v[190:193], v[174:177], v[112:115]
	v_mfma_f32_16x16x32_bf16 v[108:111], v[194:197], v[138:141], v[108:111]
	v_mfma_f32_16x16x32_bf16 v[104:107], v[194:197], v[170:173], v[104:107]
	v_mfma_f32_16x16x32_bf16 v[100:103], v[202:205], v[138:141], v[100:103]
	v_mfma_f32_16x16x32_bf16 v[96:99], v[202:205], v[170:173], v[96:99]
	v_mfma_f32_16x16x32_bf16 v[134:137], v[198:201], v[142:145], v[108:111]
	v_mfma_f32_16x16x32_bf16 v[210:213], v[198:201], v[174:177], v[104:107]
	v_mfma_f32_16x16x32_bf16 v[214:217], v[206:209], v[142:145], v[100:103]
	v_mfma_f32_16x16x32_bf16 v[218:221], v[206:209], v[174:177], v[96:99]
	s_setprio 0
	s_barrier
	s_nop 1
	ds_read_b128 v[96:99], v164
	ds_read_b128 v[100:103], v164 offset:1024
	ds_read_b128 v[104:107], v164 offset:2048
	ds_read_b128 v[108:111], v164 offset:3072
	s_barrier
	s_waitcnt lgkmcnt(0)
	s_setprio 1
	v_mfma_f32_16x16x32_bf16 v[92:95], v[178:181], v[96:99], v[92:95]
	v_mfma_f32_16x16x32_bf16 v[88:91], v[178:181], v[104:107], v[88:91]
	v_mfma_f32_16x16x32_bf16 v[84:87], v[186:189], v[96:99], v[84:87]
	v_mfma_f32_16x16x32_bf16 v[80:83], v[186:189], v[104:107], v[80:83]
	v_mfma_f32_16x16x32_bf16 v[92:95], v[182:185], v[100:103], v[92:95]
	v_mfma_f32_16x16x32_bf16 v[88:91], v[182:185], v[108:111], v[88:91]
	v_mfma_f32_16x16x32_bf16 v[84:87], v[190:193], v[100:103], v[84:87]
	v_mfma_f32_16x16x32_bf16 v[80:83], v[190:193], v[108:111], v[80:83]
	v_mfma_f32_16x16x32_bf16 v[76:79], v[194:197], v[96:99], v[76:79]
	v_mfma_f32_16x16x32_bf16 v[72:75], v[194:197], v[104:107], v[72:75]
	v_mfma_f32_16x16x32_bf16 v[68:71], v[202:205], v[96:99], v[68:71]
	v_mfma_f32_16x16x32_bf16 v[64:67], v[202:205], v[104:107], v[64:67]
	v_mfma_f32_16x16x32_bf16 v[178:181], v[198:201], v[100:103], v[76:79]
	v_mfma_f32_16x16x32_bf16 v[182:185], v[198:201], v[108:111], v[72:75]
	v_mfma_f32_16x16x32_bf16 v[186:189], v[206:209], v[100:103], v[68:71]
	v_mfma_f32_16x16x32_bf16 v[190:193], v[206:209], v[108:111], v[64:67]
	s_setprio 0
	s_barrier
	s_nop 1
	ds_read_b128 v[64:67], v163 offset:16384
	ds_read_b128 v[68:71], v163 offset:17408
	ds_read_b128 v[72:75], v129 offset:16384
	ds_read_b128 v[76:79], v129 offset:17408
	ds_read_b128 v[194:197], v131 offset:16384
	ds_read_b128 v[198:201], v131 offset:17408
	ds_read_b128 v[202:205], v132 offset:16384
	ds_read_b128 v[206:209], v132 offset:17408
	s_waitcnt vmcnt(4)
	s_barrier
	s_waitcnt lgkmcnt(0)
	s_setprio 1
	v_mfma_f32_16x16x32_bf16 v[60:63], v[64:67], v[138:141], v[60:63]
	v_mfma_f32_16x16x32_bf16 v[56:59], v[64:67], v[170:173], v[56:59]
	v_mfma_f32_16x16x32_bf16 v[52:55], v[72:75], v[138:141], v[52:55]
	v_mfma_f32_16x16x32_bf16 v[48:51], v[72:75], v[170:173], v[48:51]
	v_mfma_f32_16x16x32_bf16 v[60:63], v[68:71], v[142:145], v[60:63]
	v_mfma_f32_16x16x32_bf16 v[56:59], v[68:71], v[174:177], v[56:59]
	v_mfma_f32_16x16x32_bf16 v[52:55], v[76:79], v[142:145], v[52:55]
	v_mfma_f32_16x16x32_bf16 v[48:51], v[76:79], v[174:177], v[48:51]
	v_mfma_f32_16x16x32_bf16 v[44:47], v[194:197], v[138:141], v[44:47]
	v_mfma_f32_16x16x32_bf16 v[40:43], v[194:197], v[170:173], v[40:43]
	v_mfma_f32_16x16x32_bf16 v[36:39], v[202:205], v[138:141], v[36:39]
	v_mfma_f32_16x16x32_bf16 v[32:35], v[202:205], v[170:173], v[32:35]
	v_mfma_f32_16x16x32_bf16 v[226:229], v[198:201], v[142:145], v[44:47]
	v_mfma_f32_16x16x32_bf16 v[230:233], v[198:201], v[174:177], v[40:43]
	v_mfma_f32_16x16x32_bf16 v[138:141], v[206:209], v[142:145], v[36:39]
	v_mfma_f32_16x16x32_bf16 v[142:145], v[206:209], v[174:177], v[32:35]
	s_setprio 0
	s_setprio 1
	v_mfma_f32_16x16x32_bf16 v[28:31], v[64:67], v[96:99], v[28:31]
	v_mfma_f32_16x16x32_bf16 v[24:27], v[64:67], v[104:107], v[24:27]
	v_mfma_f32_16x16x32_bf16 v[20:23], v[72:75], v[96:99], v[20:23]
	v_mfma_f32_16x16x32_bf16 v[16:19], v[72:75], v[104:107], v[16:19]
	v_mfma_f32_16x16x32_bf16 v[28:31], v[68:71], v[100:103], v[28:31]
	v_mfma_f32_16x16x32_bf16 v[24:27], v[68:71], v[108:111], v[24:27]
	v_mfma_f32_16x16x32_bf16 v[20:23], v[76:79], v[100:103], v[20:23]
	v_mfma_f32_16x16x32_bf16 v[16:19], v[76:79], v[108:111], v[16:19]
	v_mfma_f32_16x16x32_bf16 v[12:15], v[194:197], v[96:99], v[12:15]
	v_mfma_f32_16x16x32_bf16 v[8:11], v[194:197], v[104:107], v[8:11]
	v_mfma_f32_16x16x32_bf16 v[4:7], v[202:205], v[96:99], v[4:7]
	v_mfma_f32_16x16x32_bf16 v[0:3], v[202:205], v[104:107], v[0:3]
	v_mfma_f32_16x16x32_bf16 v[168:171], v[198:201], v[100:103], v[12:15]
	v_mfma_f32_16x16x32_bf16 v[172:175], v[198:201], v[108:111], v[8:11]
	v_mfma_f32_16x16x32_bf16 v[194:197], v[206:209], v[100:103], v[4:7]
	v_mfma_f32_16x16x32_bf16 v[198:201], v[206:209], v[108:111], v[0:3]
	s_setprio 0
	s_barrier
	s_nop 1
	ds_read_b128 v[0:3], v165
	ds_read_b128 v[4:7], v165 offset:1024
	ds_read_b128 v[202:205], v165 offset:2048
	ds_read_b128 v[206:209], v165 offset:3072
	ds_read_b128 v[8:11], v163 offset:32768
	ds_read_b128 v[12:15], v163 offset:33792
	ds_read_b128 v[32:35], v129 offset:32768
	ds_read_b128 v[36:39], v129 offset:33792
	ds_read_b128 v[40:43], v131 offset:32768
	ds_read_b128 v[44:47], v131 offset:33792
	ds_read_b128 v[234:237], v132 offset:32768
	ds_read_b128 v[238:241], v132 offset:33792
	s_waitcnt vmcnt(2)
	s_barrier
	s_waitcnt lgkmcnt(0)
	s_setprio 1
	v_mfma_f32_16x16x32_bf16 v[64:67], v[8:11], v[0:3], v[124:127]
	v_mfma_f32_16x16x32_bf16 v[104:107], v[12:15], v[4:7], v[64:67]
	v_mfma_f32_16x16x32_bf16 v[64:67], v[8:11], v[202:205], v[120:123]
	v_mfma_f32_16x16x32_bf16 v[108:111], v[12:15], v[206:209], v[64:67]
	v_mfma_f32_16x16x32_bf16 v[64:67], v[32:35], v[0:3], v[116:119]
	v_mfma_f32_16x16x32_bf16 v[96:99], v[36:39], v[4:7], v[64:67]
	v_mfma_f32_16x16x32_bf16 v[64:67], v[32:35], v[202:205], v[112:115]
	v_mfma_f32_16x16x32_bf16 v[100:103], v[36:39], v[206:209], v[64:67]
	v_mfma_f32_16x16x32_bf16 v[64:67], v[40:43], v[0:3], v[134:137]
	v_mfma_f32_16x16x32_bf16 v[72:75], v[44:47], v[4:7], v[64:67]
	v_mfma_f32_16x16x32_bf16 v[64:67], v[40:43], v[202:205], v[210:213]
	v_mfma_f32_16x16x32_bf16 v[76:79], v[44:47], v[206:209], v[64:67]
	v_mfma_f32_16x16x32_bf16 v[64:67], v[234:237], v[0:3], v[214:217]
	v_mfma_f32_16x16x32_bf16 v[68:71], v[234:237], v[202:205], v[218:221]
	v_mfma_f32_16x16x32_bf16 v[64:67], v[238:241], v[4:7], v[64:67]
	v_mfma_f32_16x16x32_bf16 v[68:71], v[238:241], v[206:209], v[68:71]
	s_setprio 0
	s_barrier
	ds_read_b128 v[134:137], v166
	ds_read_b128 v[210:213], v166 offset:1024
	ds_read_b128 v[214:217], v166 offset:2048
	ds_read_b128 v[218:221], v166 offset:3072
	s_waitcnt vmcnt(0)
	s_barrier
	s_waitcnt lgkmcnt(0)
	s_setprio 1
	v_mfma_f32_16x16x32_bf16 v[92:95], v[8:11], v[134:137], v[92:95]
	v_mfma_f32_16x16x32_bf16 v[8:11], v[8:11], v[214:217], v[88:91]
	v_mfma_f32_16x16x32_bf16 v[124:127], v[12:15], v[218:221], v[8:11]
	v_mfma_f32_16x16x32_bf16 v[8:11], v[32:35], v[134:137], v[84:87]
	v_mfma_f32_16x16x32_bf16 v[112:115], v[36:39], v[210:213], v[8:11]
	v_mfma_f32_16x16x32_bf16 v[8:11], v[32:35], v[214:217], v[80:83]
	v_mfma_f32_16x16x32_bf16 v[116:119], v[36:39], v[218:221], v[8:11]
	v_mfma_f32_16x16x32_bf16 v[8:11], v[40:43], v[134:137], v[178:181]
	v_mfma_f32_16x16x32_bf16 v[88:91], v[44:47], v[210:213], v[8:11]
	v_mfma_f32_16x16x32_bf16 v[8:11], v[40:43], v[214:217], v[182:185]
	v_mfma_f32_16x16x32_bf16 v[120:123], v[12:15], v[210:213], v[92:95]
	v_mfma_f32_16x16x32_bf16 v[92:95], v[44:47], v[218:221], v[8:11]
	v_mfma_f32_16x16x32_bf16 v[8:11], v[234:237], v[134:137], v[186:189]
	v_mfma_f32_16x16x32_bf16 v[80:83], v[238:241], v[210:213], v[8:11]
	v_mfma_f32_16x16x32_bf16 v[8:11], v[234:237], v[214:217], v[190:193]
	v_mfma_f32_16x16x32_bf16 v[84:87], v[238:241], v[218:221], v[8:11]
	s_setprio 0
	s_barrier
	ds_read_b128 v[176:179], v163 offset:49152
	ds_read_b128 v[180:183], v163 offset:50176
	ds_read_b128 v[184:187], v129 offset:49152
	ds_read_b128 v[188:191], v129 offset:50176
	ds_read_b128 v[234:237], v131 offset:49152
	ds_read_b128 v[238:241], v131 offset:50176
	ds_read_b128 v[242:245], v132 offset:49152
	ds_read_b128 v[246:249], v132 offset:50176
	s_barrier
	s_waitcnt lgkmcnt(0)
	s_setprio 1
	v_mfma_f32_16x16x32_bf16 v[8:11], v[176:179], v[0:3], v[60:63]
	v_mfma_f32_16x16x32_bf16 v[40:43], v[180:183], v[4:7], v[8:11]
	v_mfma_f32_16x16x32_bf16 v[8:11], v[176:179], v[202:205], v[56:59]
	v_mfma_f32_16x16x32_bf16 v[44:47], v[180:183], v[206:209], v[8:11]
	v_mfma_f32_16x16x32_bf16 v[8:11], v[184:187], v[0:3], v[52:55]
	v_mfma_f32_16x16x32_bf16 v[32:35], v[188:191], v[4:7], v[8:11]
	v_mfma_f32_16x16x32_bf16 v[8:11], v[184:187], v[202:205], v[48:51]
	v_mfma_f32_16x16x32_bf16 v[36:39], v[188:191], v[206:209], v[8:11]
	v_mfma_f32_16x16x32_bf16 v[8:11], v[234:237], v[0:3], v[226:229]
	v_mfma_f32_16x16x32_bf16 v[0:3], v[242:245], v[0:3], v[138:141]
	v_mfma_f32_16x16x32_bf16 v[8:11], v[238:241], v[4:7], v[8:11]
	v_mfma_f32_16x16x32_bf16 v[12:15], v[234:237], v[202:205], v[230:233]
	v_mfma_f32_16x16x32_bf16 v[0:3], v[246:249], v[4:7], v[0:3]
	v_mfma_f32_16x16x32_bf16 v[4:7], v[242:245], v[202:205], v[142:145]
	v_mfma_f32_16x16x32_bf16 v[12:15], v[238:241], v[206:209], v[12:15]
	v_mfma_f32_16x16x32_bf16 v[4:7], v[246:249], v[206:209], v[4:7]
	s_setprio 0
	s_setprio 1
	v_mfma_f32_16x16x32_bf16 v[16:19], v[184:187], v[214:217], v[16:19]
	v_mfma_f32_16x16x32_bf16 v[24:27], v[176:179], v[214:217], v[24:27]
	v_mfma_f32_16x16x32_bf16 v[52:55], v[188:191], v[218:221], v[16:19]
	v_mfma_f32_16x16x32_bf16 v[16:19], v[234:237], v[134:137], v[168:171]
	v_mfma_f32_16x16x32_bf16 v[28:31], v[176:179], v[134:137], v[28:31]
	v_mfma_f32_16x16x32_bf16 v[60:63], v[180:183], v[218:221], v[24:27]
	v_mfma_f32_16x16x32_bf16 v[20:23], v[184:187], v[134:137], v[20:23]
	v_mfma_f32_16x16x32_bf16 v[24:27], v[238:241], v[210:213], v[16:19]
	v_mfma_f32_16x16x32_bf16 v[16:19], v[234:237], v[214:217], v[172:175]
	v_mfma_f32_16x16x32_bf16 v[56:59], v[180:183], v[210:213], v[28:31]
	v_mfma_f32_16x16x32_bf16 v[48:51], v[188:191], v[210:213], v[20:23]
	v_mfma_f32_16x16x32_bf16 v[28:31], v[238:241], v[218:221], v[16:19]
	v_mfma_f32_16x16x32_bf16 v[16:19], v[242:245], v[134:137], v[194:197]
	v_mfma_f32_16x16x32_bf16 v[20:23], v[242:245], v[214:217], v[198:201]
	v_mfma_f32_16x16x32_bf16 v[16:19], v[246:249], v[210:213], v[16:19]
	v_mfma_f32_16x16x32_bf16 v[20:23], v[246:249], v[218:221], v[20:23]
	s_setprio 0
	s_andn2_b64 vcc, exec, s[4:5]
	s_barrier
	s_cbranch_vccnz .LBB0_913
	s_barrier
	s_branch .LBB0_913

.LBB0_1124:
	ds_read_b128 v[176:179], v246
	ds_read_b128 v[180:183], v246 offset:1024
	ds_read_b128 v[184:187], v246 offset:2048
	ds_read_b128 v[188:191], v246 offset:3072
	v_add_u32_e32 v220, 0xc000, v231
	v_lshl_add_u64 v[212:213], s[22:23], 0, v[200:201]
	v_readfirstlane_b32 s4, v220
	v_add_u32_e32 v221, 0xe000, v231
	v_add_u32_e32 v227, s58, v230
	v_add_u32_e32 v251, s59, v230
	v_add_u32_e32 v252, s60, v230
	v_lshl_add_u64 v[160:161], v[212:213], 0, s[34:35]
	s_mov_b32 m0, s4
	v_lshl_add_u64 v[214:215], s[22:23], 0, v[202:203]
	v_readfirstlane_b32 s4, v221
	s_waitcnt lgkmcnt(0)
	ds_read_b128 v[128:131], v247
	ds_read_b128 v[136:139], v247 offset:1024
	ds_read_b128 v[132:135], v227
	ds_read_b128 v[144:147], v227 offset:1024
	ds_read_b128 v[140:143], v251
	ds_read_b128 v[152:155], v251 offset:1024
	ds_read_b128 v[148:151], v252
	ds_read_b128 v[156:159], v252 offset:1024
	global_load_lds_dwordx4 v[160:161], off
	v_lshl_add_u64 v[160:161], v[214:215], 0, s[34:35]
	s_mov_b32 m0, s4
	s_nop 0
	global_load_lds_dwordx4 v[160:161], off
	s_waitcnt lgkmcnt(8)
	s_barrier
	s_waitcnt lgkmcnt(0)
	s_setprio 1
	v_mfma_f32_16x16x32_bf16 v[124:127], v[128:131], v[176:179], v[124:127]
	v_mfma_f32_16x16x32_bf16 v[120:123], v[128:131], v[184:187], v[120:123]
	v_mfma_f32_16x16x32_bf16 v[116:119], v[132:135], v[176:179], v[116:119]
	v_mfma_f32_16x16x32_bf16 v[112:115], v[132:135], v[184:187], v[112:115]
	v_mfma_f32_16x16x32_bf16 v[108:111], v[140:143], v[176:179], v[108:111]
	v_mfma_f32_16x16x32_bf16 v[104:107], v[140:143], v[184:187], v[104:107]
	v_mfma_f32_16x16x32_bf16 v[100:103], v[148:151], v[176:179], v[100:103]
	v_mfma_f32_16x16x32_bf16 v[96:99], v[148:151], v[184:187], v[96:99]
	v_mfma_f32_16x16x32_bf16 v[124:127], v[136:139], v[180:183], v[124:127]
	v_mfma_f32_16x16x32_bf16 v[120:123], v[136:139], v[188:191], v[120:123]
	v_mfma_f32_16x16x32_bf16 v[116:119], v[144:147], v[180:183], v[116:119]
	v_mfma_f32_16x16x32_bf16 v[112:115], v[144:147], v[188:191], v[112:115]
	v_mfma_f32_16x16x32_bf16 v[108:111], v[152:155], v[180:183], v[108:111]
	v_mfma_f32_16x16x32_bf16 v[104:107], v[152:155], v[188:191], v[104:107]
	v_mfma_f32_16x16x32_bf16 v[100:103], v[156:159], v[180:183], v[100:103]
	v_mfma_f32_16x16x32_bf16 v[96:99], v[156:159], v[188:191], v[96:99]
	s_setprio 0
	s_barrier
	v_lshl_add_u64 v[204:205], s[22:23], 0, v[192:193]
	v_readfirstlane_b32 s4, v236
	v_lshl_add_u64 v[206:207], v[204:205], 0, s[36:37]
	s_mov_b32 m0, s4
	ds_read_b128 v[160:163], v248
	ds_read_b128 v[164:167], v248 offset:1024
	ds_read_b128 v[168:171], v248 offset:2048
	ds_read_b128 v[172:175], v248 offset:3072
	global_load_lds_dwordx4 v[206:207], off
	v_lshl_add_u64 v[206:207], s[22:23], 0, v[194:195]
	v_readfirstlane_b32 s4, v237
	v_lshl_add_u64 v[216:217], v[206:207], 0, s[36:37]
	s_mov_b32 m0, s4
	s_nop 0
	global_load_lds_dwordx4 v[216:217], off
	s_barrier
	s_waitcnt lgkmcnt(0)
	s_setprio 1
	v_mfma_f32_16x16x32_bf16 v[92:95], v[128:131], v[160:163], v[92:95]
	v_mfma_f32_16x16x32_bf16 v[88:91], v[128:131], v[168:171], v[88:91]
	v_mfma_f32_16x16x32_bf16 v[84:87], v[132:135], v[160:163], v[84:87]
	v_mfma_f32_16x16x32_bf16 v[80:83], v[132:135], v[168:171], v[80:83]
	v_mfma_f32_16x16x32_bf16 v[76:79], v[140:143], v[160:163], v[76:79]
	v_mfma_f32_16x16x32_bf16 v[72:75], v[140:143], v[168:171], v[72:75]
	v_mfma_f32_16x16x32_bf16 v[68:71], v[148:151], v[160:163], v[68:71]
	v_mfma_f32_16x16x32_bf16 v[64:67], v[148:151], v[168:171], v[64:67]
	v_mfma_f32_16x16x32_bf16 v[92:95], v[136:139], v[164:167], v[92:95]
	v_mfma_f32_16x16x32_bf16 v[88:91], v[136:139], v[172:175], v[88:91]
	v_mfma_f32_16x16x32_bf16 v[84:87], v[144:147], v[164:167], v[84:87]
	v_mfma_f32_16x16x32_bf16 v[80:83], v[144:147], v[172:175], v[80:83]
	v_mfma_f32_16x16x32_bf16 v[76:79], v[152:155], v[164:167], v[76:79]
	v_mfma_f32_16x16x32_bf16 v[72:75], v[152:155], v[172:175], v[72:75]
	v_mfma_f32_16x16x32_bf16 v[68:71], v[156:159], v[164:167], v[68:71]
	v_mfma_f32_16x16x32_bf16 v[64:67], v[156:159], v[172:175], v[64:67]
	s_setprio 0
	v_cndmask_b32_e64 v216, 0, 1, s[6:7]
	v_cmp_ne_u32_e64 s[4:5], 1, v216
	s_andn2_b64 vcc, exec, s[6:7]
	s_barrier
	s_cbranch_vccnz .LBB0_1126
	ds_read_b128 v[128:131], v247 offset:16384
	ds_read_b128 v[136:139], v247 offset:17408
	ds_read_b128 v[132:135], v227 offset:16384
	ds_read_b128 v[144:147], v227 offset:17408
	ds_read_b128 v[140:143], v251 offset:16384
	ds_read_b128 v[152:155], v251 offset:17408
	ds_read_b128 v[148:151], v252 offset:16384
	ds_read_b128 v[156:159], v252 offset:17408

.LBB0_1130:
	s_barrier
	ds_read_b128 v[176:179], v249
	ds_read_b128 v[180:183], v249 offset:1024
	ds_read_b128 v[184:187], v249 offset:2048
	ds_read_b128 v[188:191], v249 offset:3072
	v_readfirstlane_b32 s19, v233
	v_lshl_add_u64 v[160:161], v[212:213], 0, s[38:39]
	s_mov_b32 m0, s19
	v_readfirstlane_b32 s19, v234
	s_waitcnt lgkmcnt(0)
	ds_read_b128 v[140:143], v247 offset:32768
	ds_read_b128 v[156:159], v247 offset:33792
	ds_read_b128 v[136:139], v227 offset:32768
	ds_read_b128 v[152:155], v227 offset:33792
	ds_read_b128 v[132:135], v251 offset:32768
	ds_read_b128 v[148:151], v251 offset:33792
	ds_read_b128 v[128:131], v252 offset:32768
	ds_read_b128 v[144:147], v252 offset:33792
	global_load_lds_dwordx4 v[160:161], off
	v_lshl_add_u64 v[160:161], v[214:215], 0, s[38:39]
	s_mov_b32 m0, s19
	s_nop 0
	global_load_lds_dwordx4 v[160:161], off
	s_waitcnt lgkmcnt(8)
	s_barrier
	s_waitcnt lgkmcnt(0)
	s_setprio 1
	v_mfma_f32_16x16x32_bf16 v[124:127], v[140:143], v[176:179], v[124:127]
	v_mfma_f32_16x16x32_bf16 v[120:123], v[140:143], v[184:187], v[120:123]
	v_mfma_f32_16x16x32_bf16 v[116:119], v[136:139], v[176:179], v[116:119]
	v_mfma_f32_16x16x32_bf16 v[112:115], v[136:139], v[184:187], v[112:115]
	v_mfma_f32_16x16x32_bf16 v[108:111], v[132:135], v[176:179], v[108:111]
	v_mfma_f32_16x16x32_bf16 v[104:107], v[132:135], v[184:187], v[104:107]
	v_mfma_f32_16x16x32_bf16 v[100:103], v[128:131], v[176:179], v[100:103]
	v_mfma_f32_16x16x32_bf16 v[96:99], v[128:131], v[184:187], v[96:99]
	v_mfma_f32_16x16x32_bf16 v[124:127], v[156:159], v[180:183], v[124:127]
	v_mfma_f32_16x16x32_bf16 v[120:123], v[156:159], v[188:191], v[120:123]
	v_mfma_f32_16x16x32_bf16 v[116:119], v[152:155], v[180:183], v[116:119]
	v_mfma_f32_16x16x32_bf16 v[112:115], v[152:155], v[188:191], v[112:115]
	v_mfma_f32_16x16x32_bf16 v[108:111], v[148:151], v[180:183], v[108:111]
	v_mfma_f32_16x16x32_bf16 v[104:107], v[148:151], v[188:191], v[104:107]
	v_mfma_f32_16x16x32_bf16 v[100:103], v[144:147], v[180:183], v[100:103]
	v_mfma_f32_16x16x32_bf16 v[96:99], v[144:147], v[188:191], v[96:99]
	s_setprio 0
	s_barrier
	v_readfirstlane_b32 s19, v240
	v_lshl_add_u64 v[212:213], v[204:205], 0, s[44:45]
	s_mov_b32 m0, s19
	v_readfirstlane_b32 s19, v241
	ds_read_b128 v[160:163], v250
	ds_read_b128 v[164:167], v250 offset:1024
	ds_read_b128 v[168:171], v250 offset:2048
	ds_read_b128 v[172:175], v250 offset:3072
	global_load_lds_dwordx4 v[212:213], off
	v_lshl_add_u64 v[212:213], v[206:207], 0, s[44:45]
	s_mov_b32 m0, s19
	s_nop 0
	global_load_lds_dwordx4 v[212:213], off
	s_barrier
	s_waitcnt lgkmcnt(0)
	s_setprio 1
	v_mfma_f32_16x16x32_bf16 v[92:95], v[140:143], v[160:163], v[92:95]
	v_mfma_f32_16x16x32_bf16 v[88:91], v[140:143], v[168:171], v[88:91]
	v_mfma_f32_16x16x32_bf16 v[84:87], v[136:139], v[160:163], v[84:87]
	v_mfma_f32_16x16x32_bf16 v[80:83], v[136:139], v[168:171], v[80:83]
	v_mfma_f32_16x16x32_bf16 v[76:79], v[132:135], v[160:163], v[76:79]
	v_mfma_f32_16x16x32_bf16 v[72:75], v[132:135], v[168:171], v[72:75]
	v_mfma_f32_16x16x32_bf16 v[68:71], v[128:131], v[160:163], v[68:71]
	v_mfma_f32_16x16x32_bf16 v[64:67], v[128:131], v[168:171], v[64:67]
	v_mfma_f32_16x16x32_bf16 v[92:95], v[156:159], v[164:167], v[92:95]
	v_mfma_f32_16x16x32_bf16 v[88:91], v[156:159], v[172:175], v[88:91]
	v_mfma_f32_16x16x32_bf16 v[84:87], v[152:155], v[164:167], v[84:87]
	v_mfma_f32_16x16x32_bf16 v[80:83], v[152:155], v[172:175], v[80:83]
	v_mfma_f32_16x16x32_bf16 v[76:79], v[148:151], v[164:167], v[76:79]
	v_mfma_f32_16x16x32_bf16 v[72:75], v[148:151], v[172:175], v[72:75]
	v_mfma_f32_16x16x32_bf16 v[68:71], v[144:147], v[164:167], v[68:71]
	v_mfma_f32_16x16x32_bf16 v[64:67], v[144:147], v[172:175], v[64:67]
	s_setprio 0
	s_and_b64 vcc, exec, s[4:5]
	s_barrier
	s_cbranch_vccnz .LBB0_1132
	ds_read_b128 v[140:143], v247 offset:49152
	ds_read_b128 v[156:159], v247 offset:50176
	ds_read_b128 v[136:139], v227 offset:49152
	ds_read_b128 v[152:155], v227 offset:50176
	ds_read_b128 v[132:135], v251 offset:49152
	ds_read_b128 v[148:151], v251 offset:50176
	ds_read_b128 v[128:131], v252 offset:49152
	ds_read_b128 v[144:147], v252 offset:50176

.LBB0_1136:
	v_readfirstlane_b32 s6, v220
	s_waitcnt lgkmcnt(0)
	v_lshl_add_u64 v[128:129], v[210:211], 0, s[50:51]
	s_mov_b32 m0, s6
	v_readfirstlane_b32 s6, v221
	ds_read_b128 v[192:195], v246
	ds_read_b128 v[196:199], v246 offset:1024
	ds_read_b128 v[200:203], v246 offset:2048
	ds_read_b128 v[204:207], v246 offset:3072
	ds_read_b128 v[172:175], v247
	ds_read_b128 v[188:191], v247 offset:1024
	ds_read_b128 v[168:171], v227
	ds_read_b128 v[184:187], v227 offset:1024
	ds_read_b128 v[164:167], v251
	ds_read_b128 v[180:183], v251 offset:1024
	ds_read_b128 v[160:163], v252
	ds_read_b128 v[176:179], v252 offset:1024
	global_load_lds_dwordx4 v[128:129], off
	v_lshl_add_u64 v[128:129], v[208:209], 0, s[50:51]
	s_mov_b32 m0, s6
	s_nop 0
	global_load_lds_dwordx4 v[128:129], off
	s_barrier
	s_waitcnt lgkmcnt(0)
	s_setprio 1
	v_mfma_f32_16x16x32_bf16 v[124:127], v[172:175], v[192:195], v[124:127]
	v_mfma_f32_16x16x32_bf16 v[120:123], v[172:175], v[200:203], v[120:123]
	v_mfma_f32_16x16x32_bf16 v[116:119], v[168:171], v[192:195], v[116:119]
	v_mfma_f32_16x16x32_bf16 v[112:115], v[168:171], v[200:203], v[112:115]
	v_mfma_f32_16x16x32_bf16 v[108:111], v[164:167], v[192:195], v[108:111]
	v_mfma_f32_16x16x32_bf16 v[104:107], v[164:167], v[200:203], v[104:107]
	v_mfma_f32_16x16x32_bf16 v[100:103], v[160:163], v[192:195], v[100:103]
	v_mfma_f32_16x16x32_bf16 v[96:99], v[160:163], v[200:203], v[96:99]
	v_mfma_f32_16x16x32_bf16 v[124:127], v[188:191], v[196:199], v[124:127]
	v_mfma_f32_16x16x32_bf16 v[120:123], v[188:191], v[204:207], v[120:123]
	v_mfma_f32_16x16x32_bf16 v[116:119], v[184:187], v[196:199], v[116:119]
	v_mfma_f32_16x16x32_bf16 v[112:115], v[184:187], v[204:207], v[112:115]
	v_mfma_f32_16x16x32_bf16 v[144:147], v[180:183], v[196:199], v[108:111]
	v_mfma_f32_16x16x32_bf16 v[148:151], v[180:183], v[204:207], v[104:107]
	v_mfma_f32_16x16x32_bf16 v[152:155], v[176:179], v[196:199], v[100:103]
	v_mfma_f32_16x16x32_bf16 v[156:159], v[176:179], v[204:207], v[96:99]
	s_setprio 0
	s_barrier
	ds_read_b128 v[208:211], v248
	ds_read_b128 v[212:215], v248 offset:1024
	ds_read_b128 v[216:219], v248 offset:2048
	ds_read_b128 v[220:223], v248 offset:3072
	s_barrier
	s_waitcnt lgkmcnt(0)
	s_setprio 1
	v_mfma_f32_16x16x32_bf16 v[92:95], v[172:175], v[208:211], v[92:95]
	v_mfma_f32_16x16x32_bf16 v[88:91], v[172:175], v[216:219], v[88:91]
	v_mfma_f32_16x16x32_bf16 v[84:87], v[168:171], v[208:211], v[84:87]
	v_mfma_f32_16x16x32_bf16 v[80:83], v[168:171], v[216:219], v[80:83]
	v_mfma_f32_16x16x32_bf16 v[76:79], v[164:167], v[208:211], v[76:79]
	v_mfma_f32_16x16x32_bf16 v[72:75], v[164:167], v[216:219], v[72:75]
	v_mfma_f32_16x16x32_bf16 v[68:71], v[160:163], v[208:211], v[68:71]
	v_mfma_f32_16x16x32_bf16 v[64:67], v[160:163], v[216:219], v[64:67]
	v_mfma_f32_16x16x32_bf16 v[96:99], v[188:191], v[212:215], v[92:95]
	v_mfma_f32_16x16x32_bf16 v[100:103], v[188:191], v[220:223], v[88:91]
	v_mfma_f32_16x16x32_bf16 v[104:107], v[184:187], v[212:215], v[84:87]
	v_mfma_f32_16x16x32_bf16 v[108:111], v[184:187], v[220:223], v[80:83]
	v_mfma_f32_16x16x32_bf16 v[128:131], v[180:183], v[212:215], v[76:79]
	v_mfma_f32_16x16x32_bf16 v[132:135], v[180:183], v[220:223], v[72:75]
	v_mfma_f32_16x16x32_bf16 v[136:139], v[176:179], v[212:215], v[68:71]
	v_mfma_f32_16x16x32_bf16 v[140:143], v[176:179], v[220:223], v[64:67]
	s_setprio 0
	s_and_b64 vcc, exec, s[4:5]
	s_barrier
	s_cbranch_vccnz .LBB0_1138
	ds_read_b128 v[172:175], v247 offset:16384
	ds_read_b128 v[188:191], v247 offset:17408
	ds_read_b128 v[168:171], v227 offset:16384
	ds_read_b128 v[184:187], v227 offset:17408
	ds_read_b128 v[164:167], v251 offset:16384
	ds_read_b128 v[180:183], v251 offset:17408
	ds_read_b128 v[160:163], v252 offset:16384
	ds_read_b128 v[176:179], v252 offset:17408

.LBB0_1140:
	s_barrier
	ds_read_b128 v[192:195], v249
	ds_read_b128 v[196:199], v249 offset:1024
	ds_read_b128 v[200:203], v249 offset:2048
	ds_read_b128 v[204:207], v249 offset:3072
	s_waitcnt lgkmcnt(0)
	ds_read_b128 v[172:175], v247 offset:32768
	ds_read_b128 v[188:191], v247 offset:33792
	ds_read_b128 v[168:171], v227 offset:32768
	ds_read_b128 v[184:187], v227 offset:33792
	ds_read_b128 v[164:167], v251 offset:32768
	ds_read_b128 v[180:183], v251 offset:33792
	ds_read_b128 v[160:163], v252 offset:32768
	ds_read_b128 v[176:179], v252 offset:33792
	s_waitcnt vmcnt(2)
	s_barrier
	s_waitcnt lgkmcnt(0)
	s_setprio 1
	v_mfma_f32_16x16x32_bf16 v[64:67], v[172:175], v[192:195], v[124:127]
	v_mfma_f32_16x16x32_bf16 v[88:91], v[188:191], v[196:199], v[64:67]
	v_mfma_f32_16x16x32_bf16 v[64:67], v[172:175], v[200:203], v[120:123]
	v_mfma_f32_16x16x32_bf16 v[92:95], v[188:191], v[204:207], v[64:67]
	v_mfma_f32_16x16x32_bf16 v[64:67], v[168:171], v[192:195], v[116:119]
	v_mfma_f32_16x16x32_bf16 v[80:83], v[184:187], v[196:199], v[64:67]
	v_mfma_f32_16x16x32_bf16 v[64:67], v[168:171], v[200:203], v[112:115]
	v_mfma_f32_16x16x32_bf16 v[84:87], v[184:187], v[204:207], v[64:67]
	v_mfma_f32_16x16x32_bf16 v[64:67], v[164:167], v[192:195], v[144:147]
	v_mfma_f32_16x16x32_bf16 v[72:75], v[180:183], v[196:199], v[64:67]
	v_mfma_f32_16x16x32_bf16 v[64:67], v[164:167], v[200:203], v[148:151]
	v_mfma_f32_16x16x32_bf16 v[76:79], v[180:183], v[204:207], v[64:67]
	v_mfma_f32_16x16x32_bf16 v[64:67], v[160:163], v[192:195], v[152:155]
	v_mfma_f32_16x16x32_bf16 v[68:71], v[160:163], v[200:203], v[156:159]
	v_mfma_f32_16x16x32_bf16 v[64:67], v[176:179], v[196:199], v[64:67]
	v_mfma_f32_16x16x32_bf16 v[68:71], v[176:179], v[204:207], v[68:71]
	s_setprio 0
	s_barrier
	ds_read_b128 v[144:147], v250
	ds_read_b128 v[148:151], v250 offset:1024
	ds_read_b128 v[152:155], v250 offset:2048
	ds_read_b128 v[156:159], v250 offset:3072
	s_waitcnt vmcnt(0)
	s_barrier
	s_waitcnt lgkmcnt(0)
	s_setprio 1
	v_mfma_f32_16x16x32_bf16 v[96:99], v[172:175], v[144:147], v[96:99]
	v_mfma_f32_16x16x32_bf16 v[120:123], v[188:191], v[148:151], v[96:99]
	v_mfma_f32_16x16x32_bf16 v[96:99], v[172:175], v[152:155], v[100:103]
	v_mfma_f32_16x16x32_bf16 v[124:127], v[188:191], v[156:159], v[96:99]
	v_mfma_f32_16x16x32_bf16 v[96:99], v[168:171], v[144:147], v[104:107]
	v_mfma_f32_16x16x32_bf16 v[112:115], v[184:187], v[148:151], v[96:99]
	v_mfma_f32_16x16x32_bf16 v[96:99], v[168:171], v[152:155], v[108:111]
	v_mfma_f32_16x16x32_bf16 v[116:119], v[184:187], v[156:159], v[96:99]
	v_mfma_f32_16x16x32_bf16 v[96:99], v[164:167], v[144:147], v[128:131]
	v_mfma_f32_16x16x32_bf16 v[104:107], v[180:183], v[148:151], v[96:99]
	v_mfma_f32_16x16x32_bf16 v[96:99], v[164:167], v[152:155], v[132:135]
	v_mfma_f32_16x16x32_bf16 v[108:111], v[180:183], v[156:159], v[96:99]
	v_mfma_f32_16x16x32_bf16 v[96:99], v[160:163], v[144:147], v[136:139]
	v_mfma_f32_16x16x32_bf16 v[100:103], v[160:163], v[152:155], v[140:143]
	v_mfma_f32_16x16x32_bf16 v[96:99], v[176:179], v[148:151], v[96:99]
	v_mfma_f32_16x16x32_bf16 v[100:103], v[176:179], v[156:159], v[100:103]
	s_setprio 0
	s_and_b64 vcc, exec, s[4:5]
	s_barrier
	s_cbranch_vccnz .LBB0_1142
	ds_read_b128 v[172:175], v247 offset:49152
	ds_read_b128 v[188:191], v247 offset:50176
	ds_read_b128 v[168:171], v227 offset:49152
	ds_read_b128 v[184:187], v227 offset:50176
	ds_read_b128 v[164:167], v251 offset:49152
	ds_read_b128 v[180:183], v251 offset:50176
	ds_read_b128 v[160:163], v252 offset:49152
	ds_read_b128 v[176:179], v252 offset:50176

.LBB0_1471:
	ds_read_b128 v[166:169], v152
	ds_read_b128 v[170:173], v152 offset:1024
	ds_read_b128 v[174:177], v152 offset:2048
	ds_read_b128 v[178:181], v152 offset:3072
	v_add_u32_e32 v164, 0xc000, v144
	v_lshl_add_u64 v[222:223], s[26:27], 0, v[136:137]
	v_readfirstlane_b32 s19, v164
	v_add_u32_e32 v165, 0xe000, v144
	v_add_u32_e32 v162, s48, v141
	v_add_u32_e32 v163, s49, v141
	v_lshl_add_u64 v[214:215], v[222:223], 0, s[10:11]
	s_mov_b32 m0, s19
	v_lshl_add_u64 v[234:235], s[26:27], 0, v[138:139]
	v_readfirstlane_b32 s19, v165
	ds_read_b128 v[182:185], v153
	ds_read_b128 v[186:189], v153 offset:1024
	ds_read_b128 v[190:193], v154
	ds_read_b128 v[194:197], v154 offset:1024
	ds_read_b128 v[198:201], v162
	ds_read_b128 v[202:205], v162 offset:1024
	ds_read_b128 v[206:209], v163
	ds_read_b128 v[210:213], v163 offset:1024
	global_load_lds_dwordx4 v[214:215], off
	v_lshl_add_u64 v[214:215], v[234:235], 0, s[10:11]
	s_mov_b32 m0, s19
	s_nop 0
	global_load_lds_dwordx4 v[214:215], off
	s_waitcnt lgkmcnt(8)
	s_barrier
	s_waitcnt lgkmcnt(0)
	s_setprio 1
	v_mfma_f32_16x16x32_bf16 v[124:127], v[182:185], v[166:169], v[124:127]
	v_mfma_f32_16x16x32_bf16 v[120:123], v[182:185], v[174:177], v[120:123]
	v_mfma_f32_16x16x32_bf16 v[116:119], v[190:193], v[166:169], v[116:119]
	v_mfma_f32_16x16x32_bf16 v[112:115], v[190:193], v[174:177], v[112:115]
	v_mfma_f32_16x16x32_bf16 v[108:111], v[198:201], v[166:169], v[108:111]
	v_mfma_f32_16x16x32_bf16 v[104:107], v[198:201], v[174:177], v[104:107]
	v_mfma_f32_16x16x32_bf16 v[100:103], v[206:209], v[166:169], v[100:103]
	v_mfma_f32_16x16x32_bf16 v[96:99], v[206:209], v[174:177], v[96:99]
	v_mfma_f32_16x16x32_bf16 v[124:127], v[186:189], v[170:173], v[124:127]
	v_mfma_f32_16x16x32_bf16 v[120:123], v[186:189], v[178:181], v[120:123]
	v_mfma_f32_16x16x32_bf16 v[116:119], v[194:197], v[170:173], v[116:119]
	v_mfma_f32_16x16x32_bf16 v[112:115], v[194:197], v[178:181], v[112:115]
	v_mfma_f32_16x16x32_bf16 v[108:111], v[202:205], v[170:173], v[108:111]
	v_mfma_f32_16x16x32_bf16 v[104:107], v[202:205], v[178:181], v[104:107]
	v_mfma_f32_16x16x32_bf16 v[100:103], v[210:213], v[170:173], v[100:103]
	v_mfma_f32_16x16x32_bf16 v[96:99], v[210:213], v[178:181], v[96:99]
	s_setprio 0
	s_barrier
	v_lshl_add_u64 v[236:237], s[26:27], 0, v[132:133]
	v_readfirstlane_b32 s19, v142
	v_lshl_add_u64 v[238:239], v[236:237], 0, s[12:13]
	s_mov_b32 m0, s19
	ds_read_b128 v[214:217], v159
	ds_read_b128 v[218:221], v159 offset:1024
	ds_read_b128 v[226:229], v159 offset:2048
	ds_read_b128 v[230:233], v159 offset:3072
	global_load_lds_dwordx4 v[238:239], off
	v_lshl_add_u64 v[238:239], s[26:27], 0, v[134:135]
	v_readfirstlane_b32 s19, v143
	v_lshl_add_u64 v[240:241], v[238:239], 0, s[12:13]
	s_mov_b32 m0, s19
	s_nop 0
	global_load_lds_dwordx4 v[240:241], off
	s_barrier
	s_waitcnt lgkmcnt(0)
	s_setprio 1
	v_mfma_f32_16x16x32_bf16 v[92:95], v[182:185], v[214:217], v[92:95]
	v_mfma_f32_16x16x32_bf16 v[88:91], v[182:185], v[226:229], v[88:91]
	v_mfma_f32_16x16x32_bf16 v[84:87], v[190:193], v[214:217], v[84:87]
	v_mfma_f32_16x16x32_bf16 v[80:83], v[190:193], v[226:229], v[80:83]
	v_mfma_f32_16x16x32_bf16 v[76:79], v[198:201], v[214:217], v[76:79]
	v_mfma_f32_16x16x32_bf16 v[72:75], v[198:201], v[226:229], v[72:75]
	v_mfma_f32_16x16x32_bf16 v[68:71], v[206:209], v[214:217], v[68:71]
	v_mfma_f32_16x16x32_bf16 v[64:67], v[206:209], v[226:229], v[64:67]
	v_mfma_f32_16x16x32_bf16 v[92:95], v[186:189], v[218:221], v[92:95]
	v_mfma_f32_16x16x32_bf16 v[88:91], v[186:189], v[230:233], v[88:91]
	v_mfma_f32_16x16x32_bf16 v[84:87], v[194:197], v[218:221], v[84:87]
	v_mfma_f32_16x16x32_bf16 v[80:83], v[194:197], v[230:233], v[80:83]
	v_mfma_f32_16x16x32_bf16 v[76:79], v[202:205], v[218:221], v[76:79]
	v_mfma_f32_16x16x32_bf16 v[72:75], v[202:205], v[230:233], v[72:75]
	v_mfma_f32_16x16x32_bf16 v[68:71], v[210:213], v[218:221], v[68:71]
	v_mfma_f32_16x16x32_bf16 v[64:67], v[210:213], v[230:233], v[64:67]
	s_setprio 0
	v_readfirstlane_b32 s19, v144
	v_lshl_add_u64 v[240:241], v[222:223], 0, s[14:15]
	s_mov_b32 m0, s19
	v_readfirstlane_b32 s19, v145
	s_barrier
	ds_read_b128 v[182:185], v153 offset:16384
	ds_read_b128 v[186:189], v153 offset:17408
	ds_read_b128 v[190:193], v154 offset:16384
	ds_read_b128 v[194:197], v154 offset:17408
	ds_read_b128 v[198:201], v162 offset:16384
	ds_read_b128 v[202:205], v162 offset:17408
	ds_read_b128 v[206:209], v163 offset:16384
	ds_read_b128 v[210:213], v163 offset:17408
	global_load_lds_dwordx4 v[240:241], off
	v_lshl_add_u64 v[240:241], v[234:235], 0, s[14:15]
	s_mov_b32 m0, s19
	s_nop 0
	global_load_lds_dwordx4 v[240:241], off
	s_barrier
	s_waitcnt lgkmcnt(0)
	s_setprio 1
	v_mfma_f32_16x16x32_bf16 v[60:63], v[182:185], v[166:169], v[60:63]
	v_mfma_f32_16x16x32_bf16 v[56:59], v[182:185], v[174:177], v[56:59]
	v_mfma_f32_16x16x32_bf16 v[52:55], v[190:193], v[166:169], v[52:55]
	v_mfma_f32_16x16x32_bf16 v[48:51], v[190:193], v[174:177], v[48:51]
	v_mfma_f32_16x16x32_bf16 v[44:47], v[198:201], v[166:169], v[44:47]
	v_mfma_f32_16x16x32_bf16 v[40:43], v[198:201], v[174:177], v[40:43]
	v_mfma_f32_16x16x32_bf16 v[36:39], v[206:209], v[166:169], v[36:39]
	v_mfma_f32_16x16x32_bf16 v[32:35], v[206:209], v[174:177], v[32:35]
	v_mfma_f32_16x16x32_bf16 v[60:63], v[186:189], v[170:173], v[60:63]
	v_mfma_f32_16x16x32_bf16 v[56:59], v[186:189], v[178:181], v[56:59]
	v_mfma_f32_16x16x32_bf16 v[52:55], v[194:197], v[170:173], v[52:55]
	v_mfma_f32_16x16x32_bf16 v[48:51], v[194:197], v[178:181], v[48:51]
	v_mfma_f32_16x16x32_bf16 v[44:47], v[202:205], v[170:173], v[44:47]
	v_mfma_f32_16x16x32_bf16 v[40:43], v[202:205], v[178:181], v[40:43]
	v_mfma_f32_16x16x32_bf16 v[36:39], v[210:213], v[170:173], v[36:39]
	v_mfma_f32_16x16x32_bf16 v[32:35], v[210:213], v[178:181], v[32:35]
	s_setprio 0
	s_barrier
	v_readfirstlane_b32 s19, v146
	v_lshl_add_u64 v[166:167], v[236:237], 0, s[16:17]
	s_mov_b32 m0, s19
	v_readfirstlane_b32 s19, v147
	global_load_lds_dwordx4 v[166:167], off
	v_lshl_add_u64 v[166:167], v[238:239], 0, s[16:17]
	s_mov_b32 m0, s19
	s_nop 0
	global_load_lds_dwordx4 v[166:167], off
	s_waitcnt vmcnt(6)
	s_barrier
	s_setprio 1
	v_mfma_f32_16x16x32_bf16 v[28:31], v[182:185], v[214:217], v[28:31]
	v_mfma_f32_16x16x32_bf16 v[24:27], v[182:185], v[226:229], v[24:27]
	v_mfma_f32_16x16x32_bf16 v[20:23], v[190:193], v[214:217], v[20:23]
	v_mfma_f32_16x16x32_bf16 v[16:19], v[190:193], v[226:229], v[16:19]
	v_mfma_f32_16x16x32_bf16 v[12:15], v[198:201], v[214:217], v[12:15]
	v_mfma_f32_16x16x32_bf16 v[8:11], v[198:201], v[226:229], v[8:11]
	v_mfma_f32_16x16x32_bf16 v[4:7], v[206:209], v[214:217], v[4:7]
	v_mfma_f32_16x16x32_bf16 v[0:3], v[206:209], v[226:229], v[0:3]
	v_mfma_f32_16x16x32_bf16 v[28:31], v[186:189], v[218:221], v[28:31]
	v_mfma_f32_16x16x32_bf16 v[24:27], v[186:189], v[230:233], v[24:27]
	v_mfma_f32_16x16x32_bf16 v[20:23], v[194:197], v[218:221], v[20:23]
	v_mfma_f32_16x16x32_bf16 v[16:19], v[194:197], v[230:233], v[16:19]
	v_mfma_f32_16x16x32_bf16 v[12:15], v[202:205], v[218:221], v[12:15]
	v_mfma_f32_16x16x32_bf16 v[8:11], v[202:205], v[230:233], v[8:11]
	v_mfma_f32_16x16x32_bf16 v[4:7], v[210:213], v[218:221], v[4:7]
	v_mfma_f32_16x16x32_bf16 v[0:3], v[210:213], v[230:233], v[0:3]
	s_setprio 0
	s_barrier
	ds_read_b128 v[166:169], v160
	ds_read_b128 v[170:173], v160 offset:1024
	ds_read_b128 v[174:177], v160 offset:2048
	ds_read_b128 v[178:181], v160 offset:3072
	v_readfirstlane_b32 s19, v148
	v_lshl_add_u64 v[214:215], v[222:223], 0, s[20:21]
	s_mov_b32 m0, s19
	v_readfirstlane_b32 s19, v149
	ds_read_b128 v[182:185], v153 offset:32768
	ds_read_b128 v[186:189], v153 offset:33792
	ds_read_b128 v[190:193], v154 offset:32768
	ds_read_b128 v[194:197], v154 offset:33792
	ds_read_b128 v[198:201], v162 offset:32768
	ds_read_b128 v[202:205], v162 offset:33792
	ds_read_b128 v[206:209], v163 offset:32768
	ds_read_b128 v[210:213], v163 offset:33792
	global_load_lds_dwordx4 v[214:215], off
	v_lshl_add_u64 v[214:215], v[234:235], 0, s[20:21]
	s_mov_b32 m0, s19
	s_nop 0
	global_load_lds_dwordx4 v[214:215], off
	s_waitcnt lgkmcnt(8)
	s_barrier
	s_waitcnt lgkmcnt(0)
	s_setprio 1
	v_mfma_f32_16x16x32_bf16 v[124:127], v[182:185], v[166:169], v[124:127]
	v_mfma_f32_16x16x32_bf16 v[120:123], v[182:185], v[174:177], v[120:123]
	v_mfma_f32_16x16x32_bf16 v[116:119], v[190:193], v[166:169], v[116:119]
	v_mfma_f32_16x16x32_bf16 v[112:115], v[190:193], v[174:177], v[112:115]
	v_mfma_f32_16x16x32_bf16 v[108:111], v[198:201], v[166:169], v[108:111]
	v_mfma_f32_16x16x32_bf16 v[104:107], v[198:201], v[174:177], v[104:107]
	v_mfma_f32_16x16x32_bf16 v[100:103], v[206:209], v[166:169], v[100:103]
	v_mfma_f32_16x16x32_bf16 v[96:99], v[206:209], v[174:177], v[96:99]
	v_mfma_f32_16x16x32_bf16 v[124:127], v[186:189], v[170:173], v[124:127]
	v_mfma_f32_16x16x32_bf16 v[120:123], v[186:189], v[178:181], v[120:123]
	v_mfma_f32_16x16x32_bf16 v[116:119], v[194:197], v[170:173], v[116:119]
	v_mfma_f32_16x16x32_bf16 v[112:115], v[194:197], v[178:181], v[112:115]
	v_mfma_f32_16x16x32_bf16 v[108:111], v[202:205], v[170:173], v[108:111]
	v_mfma_f32_16x16x32_bf16 v[104:107], v[202:205], v[178:181], v[104:107]
	v_mfma_f32_16x16x32_bf16 v[100:103], v[210:213], v[170:173], v[100:103]
	v_mfma_f32_16x16x32_bf16 v[96:99], v[210:213], v[178:181], v[96:99]
	s_setprio 0
	s_barrier
	v_readfirstlane_b32 s19, v155
	v_lshl_add_u64 v[240:241], v[236:237], 0, s[22:23]
	s_mov_b32 m0, s19
	v_readfirstlane_b32 s19, v156
	ds_read_b128 v[214:217], v161
	ds_read_b128 v[218:221], v161 offset:1024
	ds_read_b128 v[226:229], v161 offset:2048
	ds_read_b128 v[230:233], v161 offset:3072
	global_load_lds_dwordx4 v[240:241], off
	v_lshl_add_u64 v[240:241], v[238:239], 0, s[22:23]
	s_mov_b32 m0, s19
	s_nop 0
	global_load_lds_dwordx4 v[240:241], off
	s_barrier
	s_waitcnt lgkmcnt(0)
	s_setprio 1
	v_mfma_f32_16x16x32_bf16 v[92:95], v[182:185], v[214:217], v[92:95]
	v_mfma_f32_16x16x32_bf16 v[88:91], v[182:185], v[226:229], v[88:91]
	v_mfma_f32_16x16x32_bf16 v[84:87], v[190:193], v[214:217], v[84:87]
	v_mfma_f32_16x16x32_bf16 v[80:83], v[190:193], v[226:229], v[80:83]
	v_mfma_f32_16x16x32_bf16 v[76:79], v[198:201], v[214:217], v[76:79]
	v_mfma_f32_16x16x32_bf16 v[72:75], v[198:201], v[226:229], v[72:75]
	v_mfma_f32_16x16x32_bf16 v[68:71], v[206:209], v[214:217], v[68:71]
	v_mfma_f32_16x16x32_bf16 v[64:67], v[206:209], v[226:229], v[64:67]
	v_mfma_f32_16x16x32_bf16 v[92:95], v[186:189], v[218:221], v[92:95]
	v_mfma_f32_16x16x32_bf16 v[88:91], v[186:189], v[230:233], v[88:91]
	v_mfma_f32_16x16x32_bf16 v[84:87], v[194:197], v[218:221], v[84:87]
	v_mfma_f32_16x16x32_bf16 v[80:83], v[194:197], v[230:233], v[80:83]
	v_mfma_f32_16x16x32_bf16 v[76:79], v[202:205], v[218:221], v[76:79]
	v_mfma_f32_16x16x32_bf16 v[72:75], v[202:205], v[230:233], v[72:75]
	v_mfma_f32_16x16x32_bf16 v[68:71], v[210:213], v[218:221], v[68:71]
	v_mfma_f32_16x16x32_bf16 v[64:67], v[210:213], v[230:233], v[64:67]
	s_setprio 0
	v_readfirstlane_b32 s19, v150
	v_lshl_add_u64 v[222:223], v[222:223], 0, s[34:35]
	s_mov_b32 m0, s19
	v_readfirstlane_b32 s19, v151
	s_barrier
	ds_read_b128 v[182:185], v153 offset:49152
	ds_read_b128 v[186:189], v153 offset:50176
	ds_read_b128 v[190:193], v154 offset:49152
	ds_read_b128 v[194:197], v154 offset:50176
	ds_read_b128 v[198:201], v162 offset:49152
	ds_read_b128 v[202:205], v162 offset:50176
	ds_read_b128 v[206:209], v163 offset:49152
	ds_read_b128 v[210:213], v163 offset:50176
	global_load_lds_dwordx4 v[222:223], off
	v_lshl_add_u64 v[222:223], v[234:235], 0, s[34:35]
	s_mov_b32 m0, s19
	s_nop 0
	global_load_lds_dwordx4 v[222:223], off
	s_barrier
	s_waitcnt lgkmcnt(0)
	s_setprio 1
	v_mfma_f32_16x16x32_bf16 v[60:63], v[182:185], v[166:169], v[60:63]
	v_mfma_f32_16x16x32_bf16 v[56:59], v[182:185], v[174:177], v[56:59]
	v_mfma_f32_16x16x32_bf16 v[52:55], v[190:193], v[166:169], v[52:55]
	v_mfma_f32_16x16x32_bf16 v[48:51], v[190:193], v[174:177], v[48:51]
	v_mfma_f32_16x16x32_bf16 v[44:47], v[198:201], v[166:169], v[44:47]
	v_mfma_f32_16x16x32_bf16 v[40:43], v[198:201], v[174:177], v[40:43]
	v_mfma_f32_16x16x32_bf16 v[36:39], v[206:209], v[166:169], v[36:39]
	v_mfma_f32_16x16x32_bf16 v[32:35], v[206:209], v[174:177], v[32:35]
	v_mfma_f32_16x16x32_bf16 v[60:63], v[186:189], v[170:173], v[60:63]
	v_mfma_f32_16x16x32_bf16 v[56:59], v[186:189], v[178:181], v[56:59]
	v_mfma_f32_16x16x32_bf16 v[52:55], v[194:197], v[170:173], v[52:55]
	v_mfma_f32_16x16x32_bf16 v[48:51], v[194:197], v[178:181], v[48:51]
	v_mfma_f32_16x16x32_bf16 v[44:47], v[202:205], v[170:173], v[44:47]
	v_mfma_f32_16x16x32_bf16 v[40:43], v[202:205], v[178:181], v[40:43]
	v_mfma_f32_16x16x32_bf16 v[36:39], v[210:213], v[170:173], v[36:39]
	v_mfma_f32_16x16x32_bf16 v[32:35], v[210:213], v[178:181], v[32:35]
	s_setprio 0
	s_barrier
	v_readfirstlane_b32 s19, v157
	v_lshl_add_u64 v[166:167], v[236:237], 0, s[36:37]
	s_mov_b32 m0, s19
	v_readfirstlane_b32 s19, v158
	global_load_lds_dwordx4 v[166:167], off
	v_lshl_add_u64 v[166:167], v[238:239], 0, s[36:37]
	s_mov_b32 m0, s19
	s_nop 0
	global_load_lds_dwordx4 v[166:167], off
	s_waitcnt vmcnt(6)
	s_barrier
	s_setprio 1
	v_mfma_f32_16x16x32_bf16 v[28:31], v[182:185], v[214:217], v[28:31]
	v_mfma_f32_16x16x32_bf16 v[24:27], v[182:185], v[226:229], v[24:27]
	v_mfma_f32_16x16x32_bf16 v[20:23], v[190:193], v[214:217], v[20:23]
	v_mfma_f32_16x16x32_bf16 v[16:19], v[190:193], v[226:229], v[16:19]
	v_mfma_f32_16x16x32_bf16 v[12:15], v[198:201], v[214:217], v[12:15]
	v_mfma_f32_16x16x32_bf16 v[8:11], v[198:201], v[226:229], v[8:11]
	v_mfma_f32_16x16x32_bf16 v[4:7], v[206:209], v[214:217], v[4:7]
	v_mfma_f32_16x16x32_bf16 v[0:3], v[206:209], v[226:229], v[0:3]
	v_mfma_f32_16x16x32_bf16 v[28:31], v[186:189], v[218:221], v[28:31]
	v_mfma_f32_16x16x32_bf16 v[24:27], v[186:189], v[230:233], v[24:27]
	v_mfma_f32_16x16x32_bf16 v[20:23], v[194:197], v[218:221], v[20:23]
	v_mfma_f32_16x16x32_bf16 v[16:19], v[194:197], v[230:233], v[16:19]
	v_mfma_f32_16x16x32_bf16 v[12:15], v[202:205], v[218:221], v[12:15]
	v_mfma_f32_16x16x32_bf16 v[8:11], v[202:205], v[230:233], v[8:11]
	v_mfma_f32_16x16x32_bf16 v[4:7], v[210:213], v[218:221], v[4:7]
	v_mfma_f32_16x16x32_bf16 v[0:3], v[210:213], v[230:233], v[0:3]
	s_setprio 0
	s_add_i32 s18, s18, 2
	s_add_u32 s26, s26, 0x100
	s_addc_u32 s27, s27, 0
	s_cmpk_lt_u32 s18, 0x54
	s_barrier
	s_cbranch_scc1 .LBB0_1471
	s_add_u32 s18, s24, 0x2b80
	s_addc_u32 s19, s25, 0
	v_readfirstlane_b32 s24, v164
	v_lshl_add_u64 v[206:207], s[18:19], 0, v[130:131]
	s_mov_b32 m0, s24
	ds_read_b128 v[132:135], v152
	ds_read_b128 v[136:139], v152 offset:1024
	ds_read_b128 v[166:169], v152 offset:2048
	ds_read_b128 v[170:173], v152 offset:3072
	ds_read_b128 v[174:177], v153
	ds_read_b128 v[178:181], v153 offset:1024
	ds_read_b128 v[182:185], v154
	ds_read_b128 v[186:189], v154 offset:1024
	ds_read_b128 v[190:193], v162
	ds_read_b128 v[194:197], v162 offset:1024
	ds_read_b128 v[198:201], v163
	ds_read_b128 v[202:205], v163 offset:1024
	global_load_lds_dwordx4 v[206:207], off
	v_lshl_add_u64 v[206:207], s[18:19], 0, v[128:129]
	v_readfirstlane_b32 s18, v165
	s_mov_b32 m0, s18
	s_nop 0
	global_load_lds_dwordx4 v[206:207], off
	s_barrier
	s_waitcnt lgkmcnt(0)
	s_setprio 1
	v_mfma_f32_16x16x32_bf16 v[124:127], v[174:177], v[132:135], v[124:127]
	v_mfma_f32_16x16x32_bf16 v[120:123], v[174:177], v[166:169], v[120:123]
	v_mfma_f32_16x16x32_bf16 v[116:119], v[182:185], v[132:135], v[116:119]
	v_mfma_f32_16x16x32_bf16 v[112:115], v[182:185], v[166:169], v[112:115]
	v_mfma_f32_16x16x32_bf16 v[124:127], v[178:181], v[136:139], v[124:127]
	v_mfma_f32_16x16x32_bf16 v[120:123], v[178:181], v[170:173], v[120:123]
	v_mfma_f32_16x16x32_bf16 v[116:119], v[186:189], v[136:139], v[116:119]
	v_mfma_f32_16x16x32_bf16 v[112:115], v[186:189], v[170:173], v[112:115]
	v_mfma_f32_16x16x32_bf16 v[108:111], v[190:193], v[132:135], v[108:111]
	v_mfma_f32_16x16x32_bf16 v[104:107], v[190:193], v[166:169], v[104:107]
	v_mfma_f32_16x16x32_bf16 v[100:103], v[198:201], v[132:135], v[100:103]
	v_mfma_f32_16x16x32_bf16 v[96:99], v[198:201], v[166:169], v[96:99]
	v_mfma_f32_16x16x32_bf16 v[206:209], v[194:197], v[136:139], v[108:111]
	v_mfma_f32_16x16x32_bf16 v[210:213], v[194:197], v[170:173], v[104:107]
	v_mfma_f32_16x16x32_bf16 v[214:217], v[202:205], v[136:139], v[100:103]
	v_mfma_f32_16x16x32_bf16 v[218:221], v[202:205], v[170:173], v[96:99]
	s_setprio 0
	s_barrier
	s_nop 1
	ds_read_b128 v[96:99], v159
	ds_read_b128 v[100:103], v159 offset:1024
	ds_read_b128 v[104:107], v159 offset:2048
	ds_read_b128 v[108:111], v159 offset:3072
	s_barrier
	s_waitcnt lgkmcnt(0)
	s_setprio 1
	v_mfma_f32_16x16x32_bf16 v[92:95], v[174:177], v[96:99], v[92:95]
	v_mfma_f32_16x16x32_bf16 v[88:91], v[174:177], v[104:107], v[88:91]
	v_mfma_f32_16x16x32_bf16 v[84:87], v[182:185], v[96:99], v[84:87]
	v_mfma_f32_16x16x32_bf16 v[80:83], v[182:185], v[104:107], v[80:83]
	v_mfma_f32_16x16x32_bf16 v[92:95], v[178:181], v[100:103], v[92:95]
	v_mfma_f32_16x16x32_bf16 v[88:91], v[178:181], v[108:111], v[88:91]
	v_mfma_f32_16x16x32_bf16 v[84:87], v[186:189], v[100:103], v[84:87]
	v_mfma_f32_16x16x32_bf16 v[80:83], v[186:189], v[108:111], v[80:83]
	v_mfma_f32_16x16x32_bf16 v[76:79], v[190:193], v[96:99], v[76:79]
	v_mfma_f32_16x16x32_bf16 v[72:75], v[190:193], v[104:107], v[72:75]
	v_mfma_f32_16x16x32_bf16 v[68:71], v[198:201], v[96:99], v[68:71]
	v_mfma_f32_16x16x32_bf16 v[64:67], v[198:201], v[104:107], v[64:67]
	v_mfma_f32_16x16x32_bf16 v[174:177], v[194:197], v[100:103], v[76:79]
	v_mfma_f32_16x16x32_bf16 v[178:181], v[194:197], v[108:111], v[72:75]
	v_mfma_f32_16x16x32_bf16 v[182:185], v[202:205], v[100:103], v[68:71]
	v_mfma_f32_16x16x32_bf16 v[186:189], v[202:205], v[108:111], v[64:67]
	s_setprio 0
	s_barrier
	s_nop 1
	ds_read_b128 v[64:67], v153 offset:16384
	ds_read_b128 v[68:71], v153 offset:17408
	ds_read_b128 v[72:75], v154 offset:16384
	ds_read_b128 v[76:79], v154 offset:17408
	ds_read_b128 v[190:193], v162 offset:16384
	ds_read_b128 v[194:197], v162 offset:17408
	ds_read_b128 v[198:201], v163 offset:16384
	ds_read_b128 v[202:205], v163 offset:17408
	s_waitcnt vmcnt(4)
	s_barrier
	s_waitcnt lgkmcnt(0)
	s_setprio 1
	v_mfma_f32_16x16x32_bf16 v[60:63], v[64:67], v[132:135], v[60:63]
	v_mfma_f32_16x16x32_bf16 v[56:59], v[64:67], v[166:169], v[56:59]
	v_mfma_f32_16x16x32_bf16 v[52:55], v[72:75], v[132:135], v[52:55]
	v_mfma_f32_16x16x32_bf16 v[48:51], v[72:75], v[166:169], v[48:51]
	v_mfma_f32_16x16x32_bf16 v[60:63], v[68:71], v[136:139], v[60:63]
	v_mfma_f32_16x16x32_bf16 v[56:59], v[68:71], v[170:173], v[56:59]
	v_mfma_f32_16x16x32_bf16 v[52:55], v[76:79], v[136:139], v[52:55]
	v_mfma_f32_16x16x32_bf16 v[48:51], v[76:79], v[170:173], v[48:51]
	v_mfma_f32_16x16x32_bf16 v[44:47], v[190:193], v[132:135], v[44:47]
	v_mfma_f32_16x16x32_bf16 v[40:43], v[190:193], v[166:169], v[40:43]
	v_mfma_f32_16x16x32_bf16 v[36:39], v[198:201], v[132:135], v[36:39]
	v_mfma_f32_16x16x32_bf16 v[32:35], v[198:201], v[166:169], v[32:35]
	v_mfma_f32_16x16x32_bf16 v[226:229], v[194:197], v[136:139], v[44:47]
	v_mfma_f32_16x16x32_bf16 v[230:233], v[194:197], v[170:173], v[40:43]
	v_mfma_f32_16x16x32_bf16 v[132:135], v[202:205], v[136:139], v[36:39]
	v_mfma_f32_16x16x32_bf16 v[136:139], v[202:205], v[170:173], v[32:35]
	s_setprio 0
	s_setprio 1
	v_mfma_f32_16x16x32_bf16 v[28:31], v[64:67], v[96:99], v[28:31]
	v_mfma_f32_16x16x32_bf16 v[24:27], v[64:67], v[104:107], v[24:27]
	v_mfma_f32_16x16x32_bf16 v[20:23], v[72:75], v[96:99], v[20:23]
	v_mfma_f32_16x16x32_bf16 v[16:19], v[72:75], v[104:107], v[16:19]
	v_mfma_f32_16x16x32_bf16 v[28:31], v[68:71], v[100:103], v[28:31]
	v_mfma_f32_16x16x32_bf16 v[24:27], v[68:71], v[108:111], v[24:27]
	v_mfma_f32_16x16x32_bf16 v[20:23], v[76:79], v[100:103], v[20:23]
	v_mfma_f32_16x16x32_bf16 v[16:19], v[76:79], v[108:111], v[16:19]
	v_mfma_f32_16x16x32_bf16 v[12:15], v[190:193], v[96:99], v[12:15]
	v_mfma_f32_16x16x32_bf16 v[8:11], v[190:193], v[104:107], v[8:11]
	v_mfma_f32_16x16x32_bf16 v[4:7], v[198:201], v[96:99], v[4:7]
	v_mfma_f32_16x16x32_bf16 v[0:3], v[198:201], v[104:107], v[0:3]
	v_mfma_f32_16x16x32_bf16 v[164:167], v[194:197], v[100:103], v[12:15]
	v_mfma_f32_16x16x32_bf16 v[168:171], v[194:197], v[108:111], v[8:11]
	v_mfma_f32_16x16x32_bf16 v[190:193], v[202:205], v[100:103], v[4:7]
	v_mfma_f32_16x16x32_bf16 v[194:197], v[202:205], v[108:111], v[0:3]
	s_setprio 0
	s_barrier
	s_nop 1
	ds_read_b128 v[0:3], v160
	ds_read_b128 v[4:7], v160 offset:1024
	ds_read_b128 v[198:201], v160 offset:2048
	ds_read_b128 v[202:205], v160 offset:3072
	ds_read_b128 v[8:11], v153 offset:32768
	ds_read_b128 v[12:15], v153 offset:33792
	ds_read_b128 v[32:35], v154 offset:32768
	ds_read_b128 v[36:39], v154 offset:33792
	ds_read_b128 v[40:43], v162 offset:32768
	ds_read_b128 v[44:47], v162 offset:33792
	ds_read_b128 v[234:237], v163 offset:32768
	ds_read_b128 v[238:241], v163 offset:33792
	s_waitcnt vmcnt(2)
	s_barrier
	s_waitcnt lgkmcnt(0)
	s_setprio 1
	v_mfma_f32_16x16x32_bf16 v[64:67], v[8:11], v[0:3], v[124:127]
	v_mfma_f32_16x16x32_bf16 v[104:107], v[12:15], v[4:7], v[64:67]
	v_mfma_f32_16x16x32_bf16 v[64:67], v[8:11], v[198:201], v[120:123]
	v_mfma_f32_16x16x32_bf16 v[108:111], v[12:15], v[202:205], v[64:67]
	v_mfma_f32_16x16x32_bf16 v[64:67], v[32:35], v[0:3], v[116:119]
	v_mfma_f32_16x16x32_bf16 v[96:99], v[36:39], v[4:7], v[64:67]
	v_mfma_f32_16x16x32_bf16 v[64:67], v[32:35], v[198:201], v[112:115]
	v_mfma_f32_16x16x32_bf16 v[100:103], v[36:39], v[202:205], v[64:67]
	v_mfma_f32_16x16x32_bf16 v[64:67], v[40:43], v[0:3], v[206:209]
	v_mfma_f32_16x16x32_bf16 v[72:75], v[44:47], v[4:7], v[64:67]
	v_mfma_f32_16x16x32_bf16 v[64:67], v[40:43], v[198:201], v[210:213]
	v_mfma_f32_16x16x32_bf16 v[76:79], v[44:47], v[202:205], v[64:67]
	v_mfma_f32_16x16x32_bf16 v[64:67], v[234:237], v[0:3], v[214:217]
	v_mfma_f32_16x16x32_bf16 v[68:71], v[234:237], v[198:201], v[218:221]
	v_mfma_f32_16x16x32_bf16 v[64:67], v[238:241], v[4:7], v[64:67]
	v_mfma_f32_16x16x32_bf16 v[68:71], v[238:241], v[202:205], v[68:71]
	s_setprio 0
	s_barrier
	ds_read_b128 v[206:209], v161
	ds_read_b128 v[210:213], v161 offset:1024
	ds_read_b128 v[214:217], v161 offset:2048
	ds_read_b128 v[218:221], v161 offset:3072
	s_waitcnt vmcnt(0)
	s_barrier
	s_waitcnt lgkmcnt(0)
	s_setprio 1
	v_mfma_f32_16x16x32_bf16 v[92:95], v[8:11], v[206:209], v[92:95]
	v_mfma_f32_16x16x32_bf16 v[8:11], v[8:11], v[214:217], v[88:91]
	v_mfma_f32_16x16x32_bf16 v[124:127], v[12:15], v[218:221], v[8:11]
	v_mfma_f32_16x16x32_bf16 v[8:11], v[32:35], v[206:209], v[84:87]
	v_mfma_f32_16x16x32_bf16 v[112:115], v[36:39], v[210:213], v[8:11]
	v_mfma_f32_16x16x32_bf16 v[8:11], v[32:35], v[214:217], v[80:83]
	v_mfma_f32_16x16x32_bf16 v[116:119], v[36:39], v[218:221], v[8:11]
	v_mfma_f32_16x16x32_bf16 v[8:11], v[40:43], v[206:209], v[174:177]
	v_mfma_f32_16x16x32_bf16 v[88:91], v[44:47], v[210:213], v[8:11]
	v_mfma_f32_16x16x32_bf16 v[8:11], v[40:43], v[214:217], v[178:181]
	v_mfma_f32_16x16x32_bf16 v[120:123], v[12:15], v[210:213], v[92:95]
	v_mfma_f32_16x16x32_bf16 v[92:95], v[44:47], v[218:221], v[8:11]
	v_mfma_f32_16x16x32_bf16 v[8:11], v[234:237], v[206:209], v[182:185]
	v_mfma_f32_16x16x32_bf16 v[80:83], v[238:241], v[210:213], v[8:11]
	v_mfma_f32_16x16x32_bf16 v[8:11], v[234:237], v[214:217], v[186:189]
	v_mfma_f32_16x16x32_bf16 v[84:87], v[238:241], v[218:221], v[8:11]
	s_setprio 0
	s_barrier
	ds_read_b128 v[172:175], v153 offset:49152
	ds_read_b128 v[176:179], v153 offset:50176
	ds_read_b128 v[180:183], v154 offset:49152
	ds_read_b128 v[184:187], v154 offset:50176
	ds_read_b128 v[234:237], v162 offset:49152
	ds_read_b128 v[238:241], v162 offset:50176
	ds_read_b128 v[242:245], v163 offset:49152
	ds_read_b128 v[246:249], v163 offset:50176
	s_barrier
	s_waitcnt lgkmcnt(0)
	s_setprio 1
	v_mfma_f32_16x16x32_bf16 v[8:11], v[172:175], v[0:3], v[60:63]
	v_mfma_f32_16x16x32_bf16 v[40:43], v[176:179], v[4:7], v[8:11]
	v_mfma_f32_16x16x32_bf16 v[8:11], v[172:175], v[198:201], v[56:59]
	v_mfma_f32_16x16x32_bf16 v[44:47], v[176:179], v[202:205], v[8:11]
	v_mfma_f32_16x16x32_bf16 v[8:11], v[180:183], v[0:3], v[52:55]
	v_mfma_f32_16x16x32_bf16 v[32:35], v[184:187], v[4:7], v[8:11]
	v_mfma_f32_16x16x32_bf16 v[8:11], v[180:183], v[198:201], v[48:51]
	v_mfma_f32_16x16x32_bf16 v[36:39], v[184:187], v[202:205], v[8:11]
	v_mfma_f32_16x16x32_bf16 v[8:11], v[234:237], v[0:3], v[226:229]
	v_mfma_f32_16x16x32_bf16 v[0:3], v[242:245], v[0:3], v[132:135]
	v_mfma_f32_16x16x32_bf16 v[8:11], v[238:241], v[4:7], v[8:11]
	v_mfma_f32_16x16x32_bf16 v[12:15], v[234:237], v[198:201], v[230:233]
	v_mfma_f32_16x16x32_bf16 v[0:3], v[246:249], v[4:7], v[0:3]
	v_mfma_f32_16x16x32_bf16 v[4:7], v[242:245], v[198:201], v[136:139]
	v_mfma_f32_16x16x32_bf16 v[12:15], v[238:241], v[202:205], v[12:15]
	v_mfma_f32_16x16x32_bf16 v[4:7], v[246:249], v[202:205], v[4:7]
	s_setprio 0
	s_setprio 1
	v_mfma_f32_16x16x32_bf16 v[16:19], v[180:183], v[214:217], v[16:19]
	v_mfma_f32_16x16x32_bf16 v[24:27], v[172:175], v[214:217], v[24:27]
	v_mfma_f32_16x16x32_bf16 v[52:55], v[184:187], v[218:221], v[16:19]
	v_mfma_f32_16x16x32_bf16 v[16:19], v[234:237], v[206:209], v[164:167]
	v_mfma_f32_16x16x32_bf16 v[28:31], v[172:175], v[206:209], v[28:31]
	v_mfma_f32_16x16x32_bf16 v[60:63], v[176:179], v[218:221], v[24:27]
	v_mfma_f32_16x16x32_bf16 v[20:23], v[180:183], v[206:209], v[20:23]
	v_mfma_f32_16x16x32_bf16 v[24:27], v[238:241], v[210:213], v[16:19]
	v_mfma_f32_16x16x32_bf16 v[16:19], v[234:237], v[214:217], v[168:171]
	v_mfma_f32_16x16x32_bf16 v[56:59], v[176:179], v[210:213], v[28:31]
	v_mfma_f32_16x16x32_bf16 v[48:51], v[184:187], v[210:213], v[20:23]
	v_mfma_f32_16x16x32_bf16 v[28:31], v[238:241], v[218:221], v[16:19]
	v_mfma_f32_16x16x32_bf16 v[16:19], v[242:245], v[206:209], v[190:193]
	v_mfma_f32_16x16x32_bf16 v[20:23], v[242:245], v[214:217], v[194:197]
	v_mfma_f32_16x16x32_bf16 v[16:19], v[246:249], v[210:213], v[16:19]
	v_mfma_f32_16x16x32_bf16 v[20:23], v[246:249], v[218:221], v[20:23]
	s_setprio 0
	s_andn2_b64 vcc, exec, s[4:5]
	s_barrier
	s_cbranch_vccnz .LBB0_1463
	s_barrier
	s_branch .LBB0_1463
